# score phase: the two sub-key tables of this workgroup's head staged once in LDS (padded rows), key fragments read by ds_read_b128 instead of per-item global loads; query-row lines touched early
# speedup vs baseline: 1.1044x; 1.0263x over previous
; __device__ __forceinline__ int tid_() { int t = threadIdx.x; asm volatile("" : "+v"(t)); return t; }
; __device__ void ph_score(const P& p, int* lds) {
;   const int lane = tid_() & 63, w = tid_() >> 6, fr = lane & 15, fq = lane >> 4;
;   const u16* Qb = p_proj;
;   int* experts = (int*)p_mix;
;   float* gates = (float*)(p_mix) + (size_t)TT * 128;
;   int* myl = lds + w * 512 + fr * 32;
;   for (int it = blockIdx.x; it < 528 * 8; it += gridDim.x) {
;     const int h = it & 7, tile = it >> 3;
;     const size_t tok = (size_t)tile * 64 + w * 16 + fr;
;     float tv[2][16];
; #pragma unroll
;     for (int half = 0; half < 2; ++half) {
;       const u16* Kb = (half ? p_K2b : p_K1b) + h * 128 * 128;
;       f32x4 sc[8];
; #pragma unroll
;       for (int mt = 0; mt < 8; ++mt) sc[mt] = f32x4{0.f, 0.f, 0.f, 0.f};
; #pragma unroll
;       for (int ks = 0; ks < 4; ++ks) {
;         bf16x8 qf = *(const bf16x8*)(Qb + tok * 2048 + h * 256 + half * 128 + ks * 32 + fq * 8);
; #pragma unroll
;         for (int mt = 0; mt < 8; ++mt) {
;           bf16x8 kf = *(const bf16x8*)(Kb + (mt * 16 + fr) * 128 + ks * 32 + fq * 8);
.LBB0_753:
	s_cmp_lt_i32 s6, 9
	s_cselect_b64 s[0:1], -1, 0
	s_cmp_gt_i32 s7, 8
	s_cselect_b64 s[2:3], -1, 0
	s_and_b64 s[0:1], s[0:1], s[2:3]
	s_andn2_b64 vcc, exec, s[0:1]
	s_cbranch_vccnz .LBB0_911
	v_readlane_b32 s0, v228, 0
	v_mov_b32_e32 v0, v220
	v_mov_b32_e32 v1, v220
	s_cmpk_gt_i32 s0, 0x107f
	v_readlane_b32 s1, v228, 1
	s_cbranch_scc1 .LBB0_857
	v_readlane_b32 s86, v228, 0
	v_readlane_b32 s84, v228, 8
	v_readlane_b32 s85, v228, 9
	s_and_b32 s86, s86, 7
	s_lshl_b32 s86, s86, 15
	s_add_u32 s84, s84, 0xe40000
	s_addc_u32 s85, s85, 0
	s_add_u32 s84, s84, s86
	s_addc_u32 s85, s85, 0
	s_mov_b32 s87, s84
	v_lshlrev_b32_e32 v218, 4, v220
	v_lshrrev_b32_e32 v219, 4, v220
	v_and_b32_e32 v221, 15, v220
	v_mul_u32_u24_e32 v219, 0x110, v219
	v_lshl_add_u32 v219, v221, 4, v219
	v_add_u32_e32 v222, 0x8000, v219
	global_load_dwordx4 v[154:157], v218, s[84:85]
	s_add_u32 s84, s84, 0x1000
	s_addc_u32 s85, s85, 0
	global_load_dwordx4 v[158:161], v218, s[84:85]
	s_add_u32 s84, s84, 0x1000
	s_addc_u32 s85, s85, 0
	global_load_dwordx4 v[162:165], v218, s[84:85]
	s_add_u32 s84, s84, 0x1000
	s_addc_u32 s85, s85, 0
	global_load_dwordx4 v[166:169], v218, s[84:85]
	s_add_u32 s84, s84, 0x1000
	s_addc_u32 s85, s85, 0
	global_load_dwordx4 v[170:173], v218, s[84:85]
	s_add_u32 s84, s84, 0x1000
	s_addc_u32 s85, s85, 0
	global_load_dwordx4 v[174:177], v218, s[84:85]
	s_add_u32 s84, s84, 0x1000
	s_addc_u32 s85, s85, 0
	global_load_dwordx4 v[178:181], v218, s[84:85]
	s_add_u32 s84, s84, 0x1000
	s_addc_u32 s85, s85, 0
	global_load_dwordx4 v[182:185], v218, s[84:85]
	s_add_u32 s84, s84, 0x39000
	s_addc_u32 s85, s85, 0
	global_load_dwordx4 v[186:189], v218, s[84:85]
	s_add_u32 s84, s84, 0x1000
	s_addc_u32 s85, s85, 0
	global_load_dwordx4 v[190:193], v218, s[84:85]
	s_add_u32 s84, s84, 0x1000
	s_addc_u32 s85, s85, 0
	global_load_dwordx4 v[194:197], v218, s[84:85]
	s_add_u32 s84, s84, 0x1000
	s_addc_u32 s85, s85, 0
	global_load_dwordx4 v[198:201], v218, s[84:85]
	s_add_u32 s84, s84, 0x1000
	s_addc_u32 s85, s85, 0
	global_load_dwordx4 v[202:205], v218, s[84:85]
	s_add_u32 s84, s84, 0x1000
	s_addc_u32 s85, s85, 0
	global_load_dwordx4 v[206:209], v218, s[84:85]
	s_add_u32 s84, s84, 0x1000
	s_addc_u32 s85, s85, 0
	global_load_dwordx4 v[210:213], v218, s[84:85]
	s_add_u32 s84, s84, 0x1000
	s_addc_u32 s85, s85, 0
	global_load_dwordx4 v[214:217], v218, s[84:85]
	s_waitcnt vmcnt(0)
	ds_write_b128 v219, v[154:157] offset:8192
	ds_write_b128 v219, v[158:161] offset:12544
	ds_write_b128 v219, v[162:165] offset:16896
	ds_write_b128 v219, v[166:169] offset:21248
	ds_write_b128 v219, v[170:173] offset:25600
	ds_write_b128 v219, v[174:177] offset:29952
	ds_write_b128 v219, v[178:181] offset:34304
	ds_write_b128 v219, v[182:185] offset:38656
	ds_write_b128 v222, v[186:189] offset:10448
	ds_write_b128 v222, v[190:193] offset:14800
	ds_write_b128 v222, v[194:197] offset:19152
	ds_write_b128 v222, v[198:201] offset:23504
	ds_write_b128 v222, v[202:205] offset:27856
	ds_write_b128 v222, v[206:209] offset:32208
	ds_write_b128 v222, v[210:213] offset:36560
	ds_write_b128 v222, v[214:217] offset:40912
	s_waitcnt lgkmcnt(0)
	s_barrier
; __device__ __forceinline__ int tid_() { int t = threadIdx.x; asm volatile("" : "+v"(t)); return t; }
; __device__ void ph_score(const P& p, int* lds) {
;   const int lane = tid_() & 63, w = tid_() >> 6, fr = lane & 15, fq = lane >> 4;
;   const u16* Qb = p_proj;
;   int* experts = (int*)p_mix;
;   float* gates = (float*)(p_mix) + (size_t)TT * 128;
;   int* myl = lds + w * 512 + fr * 32;
;   for (int it = blockIdx.x; it < 528 * 8; it += gridDim.x) {
;     const int h = it & 7, tile = it >> 3;
;     const size_t tok = (size_t)tile * 64 + w * 16 + fr;
;     float tv[2][16];
	s_mov_b32 s84, s87
	s_add_u32 s85, s87, 0x40000
	v_readlane_b32 s4, v228, 2
	v_and_b32_e32 v2, 15, v0
	v_readlane_b32 s10, v228, 8
	v_ashrrev_i32_e32 v1, 6, v1
	s_waitcnt vmcnt(0)
	v_bfe_u32 v21, v0, 4, 2
	v_readlane_b32 s11, v228, 9
	s_add_u32 s2, s10, 0x8140000
	v_lshlrev_b32_e32 v0, 7, v2
	s_addc_u32 s3, s11, 0
	v_lshl_or_b32 v49, v1, 11, v0
	v_lshlrev_b32_e32 v1, 4, v1
	s_add_u32 s60, s10, 0x137c8000
	v_ashrrev_i32_e32 v17, 31, v1
	v_or_b32_e32 v16, v1, v2
	v_mbcnt_lo_u32_b32 v1, -1, 0
	s_addc_u32 s61, s11, 0
	v_mbcnt_hi_u32_b32 v1, -1, v1
	s_add_u32 s68, s10, 0x14848000
	v_mov_b32_e32 v19, 0
	v_and_b32_e32 v4, 64, v1
	v_lshlrev_b32_e32 v18, 4, v21
	s_addc_u32 s69, s11, 0
	v_xor_b32_e32 v3, 32, v1
	v_add_u32_e32 v4, 64, v4
	v_lshl_add_u64 v[24:25], s[10:11], 0, v[18:19]
	s_mov_b64 s[10:11], 0xe40000
	v_cmp_lt_i32_e32 vcc, v3, v4
	v_lshl_add_u64 v[22:23], v[24:25], 0, s[10:11]
	s_mov_b64 s[10:11], 0xe80000
	v_readlane_b32 s5, v228, 3
	v_readlane_b32 s6, v228, 4
	v_readlane_b32 s7, v228, 5
	v_readlane_b32 s8, v228, 6
	v_readlane_b32 s9, v228, 7
	v_lshlrev_b32_e32 v2, 3, v21
	v_lshlrev_b32_e32 v20, 2, v21
	v_cndmask_b32_e32 v1, v1, v3, vcc
	v_lshlrev_b32_e32 v55, 6, v21
	v_or_b32_e32 v4, 0x800, v0
	v_or_b32_e32 v6, 0x1000, v0
	v_or_b32_e32 v8, 0x1800, v0
	v_or_b32_e32 v10, 0x2000, v0
	v_or_b32_e32 v12, 0x2800, v0
	v_or_b32_e32 v14, 0x3000, v0
	v_or_b32_e32 v42, 0x3800, v0
	v_lshl_add_u64 v[24:25], v[24:25], 0, s[10:11]
	v_readlane_b32 s10, v228, 0
	s_mov_b32 s71, 0
	v_lshlrev_b32_e32 v54, 2, v1
	v_cmp_eq_u32_e64 s[0:1], 3, v21
	v_cmp_eq_u32_e64 s[4:5], 2, v21
	v_cmp_eq_u32_e64 s[6:7], 1, v21
	v_cmp_ne_u32_e64 s[8:9], 0, v21
	v_or_b32_e32 v56, 64, v20
	v_or_b32_e32 v57, 1, v20
	v_or_b32_e32 v58, 0x41, v20
	v_or_b32_e32 v59, 2, v20
	v_or_b32_e32 v60, 0x42, v20
	v_or_b32_e32 v61, 3, v20
	v_or_b32_e32 v62, 0x43, v20
	v_or_b32_e32 v63, 16, v20
	v_or_b32_e32 v64, 0x50, v20
	v_or_b32_e32 v65, 17, v20
	v_or_b32_e32 v66, 0x51, v20
	v_or_b32_e32 v67, 18, v20
	v_or_b32_e32 v68, 0x52, v20
	v_or_b32_e32 v69, 19, v20
	v_or_b32_e32 v70, 0x53, v20
	v_or_b32_e32 v71, 32, v20
	v_or_b32_e32 v72, 0x60, v20
	v_or_b32_e32 v73, 33, v20
	v_or_b32_e32 v74, 0x61, v20
	v_or_b32_e32 v75, 34, v20
	v_or_b32_e32 v76, 0x62, v20
	v_or_b32_e32 v77, 35, v20
	v_or_b32_e32 v78, 0x63, v20
	v_or_b32_e32 v79, 48, v20
	v_or_b32_e32 v80, 0x70, v20
	v_or_b32_e32 v81, 49, v20
	v_or_b32_e32 v82, 0x71, v20
	v_or_b32_e32 v83, 50, v20
	v_or_b32_e32 v84, 0x72, v20
	v_or_b32_e32 v85, 51, v20
	v_or_b32_e32 v86, 0x73, v20
	v_or_b32_e32 v87, 1, v55
	v_or_b32_e32 v88, 2, v55
	v_or_b32_e32 v89, 3, v55
	v_or_b32_e32 v90, 4, v55
	v_or_b32_e32 v91, 5, v55
	v_or_b32_e32 v92, 6, v55
	v_or_b32_e32 v93, 7, v55
	v_or_b32_e32 v94, 8, v55
	v_or_b32_e32 v95, 9, v55
	v_or_b32_e32 v96, 10, v55
	v_or_b32_e32 v97, 11, v55
	v_or_b32_e32 v98, 12, v55
	v_or_b32_e32 v99, 13, v55
	v_or_b32_e32 v100, 14, v55
	v_or_b32_e32 v101, 15, v55
	v_or_b32_e32 v102, 31, v55
	v_or_b32_e32 v103, 30, v55
	v_or_b32_e32 v104, 29, v55
	v_or_b32_e32 v105, 28, v55
	v_or_b32_e32 v106, 27, v55
	v_or_b32_e32 v107, 26, v55
	v_or_b32_e32 v108, 25, v55
	v_or_b32_e32 v109, 24, v55
	v_or_b32_e32 v110, 23, v55
	v_or_b32_e32 v111, 22, v55
	v_or_b32_e32 v112, 21, v55
	v_or_b32_e32 v113, 20, v55
	v_or_b32_e32 v114, 19, v55
	v_or_b32_e32 v115, 18, v55
	v_or_b32_e32 v116, 17, v55
	v_or_b32_e32 v117, 16, v55
	v_or_b32_e32 v118, 47, v55
	v_or_b32_e32 v119, 46, v55
	v_or_b32_e32 v120, 45, v55
	v_or_b32_e32 v121, 44, v55
	v_or_b32_e32 v122, 43, v55
	v_or_b32_e32 v123, 42, v55
	v_or_b32_e32 v124, 41, v55
	v_or_b32_e32 v125, 40, v55
	v_or_b32_e32 v126, 39, v55
	v_or_b32_e32 v127, 38, v55
	v_or_b32_e32 v128, 37, v55
	v_or_b32_e32 v129, 36, v55
	v_or_b32_e32 v130, 35, v55
	v_or_b32_e32 v131, 34, v55
	v_or_b32_e32 v132, 33, v55
	v_or_b32_e32 v133, 32, v55
	v_or_b32_e32 v134, 63, v55
	v_or_b32_e32 v135, 55, v55
	v_or_b32_e32 v136, 59, v55
	v_or_b32_e32 v137, 51, v55
	v_or_b32_e32 v138, 61, v55
	v_or_b32_e32 v139, 53, v55
	v_or_b32_e32 v140, 57, v55
	v_or_b32_e32 v141, 49, v55
	v_or_b32_e32 v142, 62, v55
	v_or_b32_e32 v143, 54, v55
	v_or_b32_e32 v144, 58, v55
	v_or_b32_e32 v145, 50, v55
	v_or_b32_e32 v146, 60, v55
	v_or_b32_e32 v147, 52, v55
	v_or_b32_e32 v148, 56, v55
	v_or_b32_e32 v149, 48, v55
	v_lshlrev_b32_e32 v26, 1, v2
	v_mov_b32_e32 v27, v19
	v_lshlrev_b32_e32 v28, 1, v0
	v_mov_b32_e32 v29, v19
	v_lshlrev_b32_e32 v30, 1, v4
	v_mov_b32_e32 v31, v19
	v_lshlrev_b32_e32 v32, 1, v6
	v_mov_b32_e32 v33, v19
	v_lshlrev_b32_e32 v34, 1, v8
	v_mov_b32_e32 v35, v19
	v_lshlrev_b32_e32 v36, 1, v10
	v_mov_b32_e32 v37, v19
	v_lshlrev_b32_e32 v38, 1, v12
	v_mov_b32_e32 v39, v19
	v_lshlrev_b32_e32 v40, 1, v14
	v_mov_b32_e32 v41, v19
	v_lshlrev_b32_e32 v42, 1, v42
	v_mov_b32_e32 v43, v19
	s_mov_b64 s[72:73], 0x80
	s_mov_b64 s[76:77], 0xc0
	s_movk_i32 s33, 0xff80
	s_brev_b32 s75, -2
	s_movk_i32 s80, 0x7f
	v_add_u32_e32 v150, v49, v18
	s_movk_i32 s81, 0xff00
	v_mov_b32_e32 v151, 0x7fffff80
	v_mov_b32_e32 v152, 0x7fffff00
	s_mov_b32 s82, s10
	v_readlane_b32 s11, v228, 1
	s_branch .LBB0_758

; __device__ __forceinline__ f32x4 mfma16(bf16x8 a, bf16x8 b, f32x4 c) { return __builtin_amdgcn_mfma_f32_16x16x32_bf16(a, b, c, 0, 0, 0); }
; __device__ void ph_score(const P& p, int* lds) {
;     ...
;     for (int half = 0; half < 2; ++half) {
;       const u16* Kb = (half ? p_K2b : p_K1b) + h * 128 * 128;
;       f32x4 sc[8];
; #pragma unroll
;       for (int mt = 0; mt < 8; ++mt) sc[mt] = f32x4{0.f, 0.f, 0.f, 0.f};
; #pragma unroll
;       for (int ks = 0; ks < 4; ++ks) {
;         bf16x8 qf = *(const bf16x8*)(Qb + tok * 2048 + h * 256 + half * 128 + ks * 32 + fq * 8);
; #pragma unroll
;         for (int mt = 0; mt < 8; ++mt) {
;           bf16x8 kf = *(const bf16x8*)(Kb + (mt * 16 + fr) * 128 + ks * 32 + fq * 8);
;           sc[mt] = mfma16(kf, qf, sc[mt]);
;         }
;       }
.LBB0_758:
	s_ashr_i32 s10, s82, 3
	s_ashr_i32 s11, s10, 31
	s_lshl_b64 s[10:11], s[10:11], 6
	v_lshl_add_u64 v[44:45], s[10:11], 0, v[16:17]
	s_and_b32 s83, s82, 7
	v_lshlrev_b64 v[0:1], 12, v[44:45]
	v_lshl_add_u64 v[0:1], s[2:3], 0, v[0:1]
	s_lshl_b32 s70, s83, 9
	v_lshl_add_u64 v[0:1], v[0:1], 0, s[70:71]
	s_lshl_b32 s70, s83, 15
	v_lshl_add_u64 v[14:15], v[22:23], 0, s[70:71]
	v_lshl_add_u64 v[46:47], v[14:15], 0, v[28:29]
	v_lshl_add_u64 v[0:1], v[0:1], 0, v[26:27]
	v_lshl_add_u64 v[10:11], v[14:15], 0, v[30:31]
	v_lshl_add_u64 v[50:51], v[14:15], 0, v[32:33]
	v_lshl_add_u64 v[154:155], v[14:15], 0, v[34:35]
	v_lshl_add_u64 v[166:167], v[14:15], 0, v[36:37]
	v_lshl_add_u64 v[170:171], v[14:15], 0, v[38:39]
	v_lshl_add_u64 v[174:175], v[14:15], 0, v[40:41]
	v_lshl_add_u64 v[178:179], v[14:15], 0, v[42:43]
	v_subrev_u32_e32 v2, s84, v46
	v_lshrrev_b32_e32 v3, 8, v2
	v_lshl_add_u32 v2, v3, 4, v2
	ds_read_b128 v[2:5], v2 offset:8192
	global_load_dwordx4 v[6:9], v[0:1], off
	global_load_dword v218, v[0:1], off offset:128
	global_load_dword v219, v[0:1], off offset:256
	global_load_dword v225, v[0:1], off offset:384
	v_lshl_add_u64 v[194:195], v[14:15], 0, 64
	v_subrev_u32_e32 v10, s84, v10
	v_lshrrev_b32_e32 v11, 8, v10
	v_lshl_add_u32 v10, v11, 4, v10
	ds_read_b128 v[10:13], v10 offset:8192
	v_lshl_add_u64 v[182:183], v[194:195], 0, v[30:31]
	v_subrev_u32_e32 v50, s84, v50
	v_lshrrev_b32_e32 v51, 8, v50
	v_lshl_add_u32 v50, v51, 4, v50
	ds_read_b128 v[50:53], v50 offset:8192
	v_lshl_add_u64 v[186:187], v[194:195], 0, v[32:33]
	v_subrev_u32_e32 v154, s84, v154
	v_lshrrev_b32_e32 v155, 8, v154
	v_lshl_add_u32 v154, v155, 4, v154
	ds_read_b128 v[154:157], v154 offset:8192
	s_nop 0
	global_load_dwordx4 v[158:161], v[0:1], off offset:64
	v_subrev_u32_e32 v162, s84, v46
	v_lshrrev_b32_e32 v163, 8, v162
	v_lshl_add_u32 v162, v163, 4, v162
	ds_read_b128 v[162:165], v162 offset:8256
	v_lshl_add_u64 v[190:191], v[194:195], 0, v[34:35]
	v_subrev_u32_e32 v166, s84, v166
	v_lshrrev_b32_e32 v167, 8, v166
	v_lshl_add_u32 v166, v167, 4, v166
	ds_read_b128 v[166:169], v166 offset:8192
	v_lshl_add_u64 v[196:197], v[194:195], 0, v[36:37]
	v_subrev_u32_e32 v170, s84, v170
	v_lshrrev_b32_e32 v171, 8, v170
	v_lshl_add_u32 v170, v171, 4, v170
	ds_read_b128 v[170:173], v170 offset:8192
	v_lshl_add_u64 v[202:203], v[14:15], 0, s[72:73]
	v_subrev_u32_e32 v174, s84, v174
	v_lshrrev_b32_e32 v175, 8, v174
	v_lshl_add_u32 v174, v175, 4, v174
	ds_read_b128 v[174:177], v174 offset:8192
	v_lshl_add_u64 v[198:199], v[202:203], 0, v[30:31]
	v_subrev_u32_e32 v178, s84, v178
	v_lshrrev_b32_e32 v179, 8, v178
	v_lshl_add_u32 v178, v179, 4, v178
	ds_read_b128 v[178:181], v178 offset:8192
	v_lshl_add_u64 v[204:205], v[202:203], 0, v[36:37]
	v_subrev_u32_e32 v182, s84, v182
	v_lshrrev_b32_e32 v183, 8, v182
	v_lshl_add_u32 v182, v183, 4, v182
	ds_read_b128 v[182:185], v182 offset:8192
	v_lshl_add_u64 v[14:15], v[14:15], 0, s[76:77]
	v_subrev_u32_e32 v186, s84, v186
	v_lshrrev_b32_e32 v187, 8, v186
	v_lshl_add_u32 v186, v187, 4, v186
	ds_read_b128 v[186:189], v186 offset:8192
	s_waitcnt vmcnt(0) lgkmcnt(0)
	v_mfma_f32_16x16x32_bf16 v[2:5], v[2:5], v[6:9], 0
	v_subrev_u32_e32 v190, s84, v190
	v_lshrrev_b32_e32 v191, 8, v190
	v_lshl_add_u32 v190, v191, 4, v190
	ds_read_b128 v[190:193], v190 offset:8192
	v_mfma_f32_16x16x32_bf16 v[10:13], v[10:13], v[6:9], 0
	v_mfma_f32_16x16x32_bf16 v[50:53], v[50:53], v[6:9], 0
	v_mfma_f32_16x16x32_bf16 v[154:157], v[154:157], v[6:9], 0
	v_mfma_f32_16x16x32_bf16 v[166:169], v[166:169], v[6:9], 0
	v_mfma_f32_16x16x32_bf16 v[170:173], v[170:173], v[6:9], 0
	v_mfma_f32_16x16x32_bf16 v[174:177], v[174:177], v[6:9], 0
	v_mfma_f32_16x16x32_bf16 v[6:9], v[178:181], v[6:9], 0
	v_subrev_u32_e32 v178, s84, v196
	v_lshrrev_b32_e32 v179, 8, v178
	v_lshl_add_u32 v178, v179, 4, v178
	ds_read_b128 v[178:181], v178 offset:8192
	v_lshl_add_u64 v[196:197], v[194:195], 0, v[38:39]
	v_mfma_f32_16x16x32_bf16 v[2:5], v[162:165], v[158:161], v[2:5]
	v_subrev_u32_e32 v162, s84, v196
	v_lshrrev_b32_e32 v163, 8, v162
	v_lshl_add_u32 v162, v163, 4, v162
	ds_read_b128 v[162:165], v162 offset:8192
	v_lshl_add_u64 v[196:197], v[194:195], 0, v[40:41]
	v_lshl_add_u64 v[194:195], v[194:195], 0, v[42:43]
	v_mfma_f32_16x16x32_bf16 v[10:13], v[182:185], v[158:161], v[10:13]
	v_subrev_u32_e32 v182, s84, v196
	v_lshrrev_b32_e32 v183, 8, v182
	v_lshl_add_u32 v182, v183, 4, v182
	ds_read_b128 v[182:185], v182 offset:8192
	v_mfma_f32_16x16x32_bf16 v[50:53], v[186:189], v[158:161], v[50:53]
	v_subrev_u32_e32 v186, s84, v194
	v_lshrrev_b32_e32 v187, 8, v186
	v_lshl_add_u32 v186, v187, 4, v186
	ds_read_b128 v[186:189], v186 offset:8192
	s_nop 0
	v_subrev_u32_e32 v194, s84, v46
	v_lshrrev_b32_e32 v195, 8, v194
	v_lshl_add_u32 v194, v195, 4, v194
	ds_read_b128 v[194:197], v194 offset:8320
	s_waitcnt vmcnt(0) lgkmcnt(0)
	v_mfma_f32_16x16x32_bf16 v[154:157], v[190:193], v[158:161], v[154:157]
	global_load_dwordx4 v[190:193], v[0:1], off offset:128
	v_mfma_f32_16x16x32_bf16 v[166:169], v[178:181], v[158:161], v[166:169]
	v_subrev_u32_e32 v178, s84, v198
	v_lshrrev_b32_e32 v179, 8, v178
	v_lshl_add_u32 v178, v179, 4, v178
	ds_read_b128 v[178:181], v178 offset:8192
	v_lshl_add_u64 v[198:199], v[202:203], 0, v[32:33]
	v_mfma_f32_16x16x32_bf16 v[162:165], v[162:165], v[158:161], v[170:173]
	s_nop 2
	v_subrev_u32_e32 v170, s84, v198
	v_lshrrev_b32_e32 v171, 8, v170
	v_lshl_add_u32 v170, v171, 4, v170
	ds_read_b128 v[170:173], v170 offset:8192
	v_lshl_add_u64 v[198:199], v[202:203], 0, v[34:35]
	v_mfma_f32_16x16x32_bf16 v[174:177], v[182:185], v[158:161], v[174:177]
	v_subrev_u32_e32 v182, s84, v198
	v_lshrrev_b32_e32 v183, 8, v182
	v_lshl_add_u32 v182, v183, 4, v182
	ds_read_b128 v[182:185], v182 offset:8192
	s_nop 0
	global_load_dwordx4 v[198:201], v[0:1], off offset:192
	v_mfma_f32_16x16x32_bf16 v[6:9], v[186:189], v[158:161], v[6:9]
	v_subrev_u32_e32 v186, s84, v46
	v_lshrrev_b32_e32 v187, 8, v186
	v_lshl_add_u32 v186, v187, 4, v186
	ds_read_b128 v[186:189], v186 offset:8384
	v_lshl_add_u64 v[46:47], v[202:203], 0, v[40:41]
	v_subrev_u32_e32 v158, s84, v204
	v_lshrrev_b32_e32 v159, 8, v158
	v_lshl_add_u32 v158, v159, 4, v158
	ds_read_b128 v[158:161], v158 offset:8192
	s_waitcnt vmcnt(0) lgkmcnt(0)
; __device__ __forceinline__ f32x4 mfma16(bf16x8 a, bf16x8 b, f32x4 c) { return __builtin_amdgcn_mfma_f32_16x16x32_bf16(a, b, c, 0, 0, 0); }
; __device__ void ph_score(const P& p, int* lds) {
;     ...
;       for (int ks = 0; ks < 4; ++ks) {
;         bf16x8 qf = *(const bf16x8*)(Qb + tok * 2048 + h * 256 + half * 128 + ks * 32 + fq * 8);
; #pragma unroll
;         for (int mt = 0; mt < 8; ++mt) {
;           bf16x8 kf = *(const bf16x8*)(Kb + (mt * 16 + fr) * 128 + ks * 32 + fq * 8);
;           sc[mt] = mfma16(kf, qf, sc[mt]);
;         }
;       }
;       int a[16], b[16];
; #pragma unroll
;       for (int mt = 0; mt < 4; ++mt)
; #pragma unroll
;         for (int r = 0; r < 4; ++r) {
;           a[mt * 4 + r] = key_pack(sc[mt][r], mt * 16 + fq * 4 + r, 0x7f);
;           b[mt * 4 + r] = key_pack(sc[mt + 4][r], (mt + 4) * 16 + fq * 4 + r, 0x7f);
;         }
	v_mfma_f32_16x16x32_bf16 v[2:5], v[194:197], v[190:193], v[2:5]
	v_mfma_f32_16x16x32_bf16 v[10:13], v[178:181], v[190:193], v[10:13]
	v_subrev_u32_e32 v178, s84, v46
	v_lshrrev_b32_e32 v179, 8, v178
	v_lshl_add_u32 v178, v179, 4, v178
	ds_read_b128 v[178:181], v178 offset:8192
	v_lshl_add_u64 v[204:205], v[202:203], 0, v[38:39]
	v_subrev_u32_e32 v194, s84, v204
	v_lshrrev_b32_e32 v195, 8, v194
	v_lshl_add_u32 v194, v195, 4, v194
	ds_read_b128 v[194:197], v194 offset:8192
	v_lshl_add_u64 v[46:47], v[202:203], 0, v[42:43]
	v_mfma_f32_16x16x32_bf16 v[50:53], v[170:173], v[190:193], v[50:53]
	v_subrev_u32_e32 v170, s84, v46
	v_lshrrev_b32_e32 v171, 8, v170
	v_lshl_add_u32 v170, v171, 4, v170
	ds_read_b128 v[170:173], v170 offset:8192
	v_lshl_add_u64 v[46:47], v[14:15], 0, v[30:31]
	v_mfma_f32_16x16x32_bf16 v[154:157], v[182:185], v[190:193], v[154:157]
	v_subrev_u32_e32 v182, s84, v46
	v_lshrrev_b32_e32 v183, 8, v182
	v_lshl_add_u32 v182, v183, 4, v182
	ds_read_b128 v[182:185], v182 offset:8192
	v_lshl_add_u64 v[46:47], v[14:15], 0, v[32:33]
	v_mfma_f32_16x16x32_bf16 v[158:161], v[158:161], v[190:193], v[166:169]
	s_nop 2
	v_subrev_u32_e32 v166, s84, v46
	v_lshrrev_b32_e32 v167, 8, v166
	v_lshl_add_u32 v166, v167, 4, v166
	ds_read_b128 v[166:169], v166 offset:8192
	v_lshl_add_u64 v[46:47], v[14:15], 0, v[36:37]
	v_mfma_f32_16x16x32_bf16 v[2:5], v[186:189], v[198:201], v[2:5]
	s_waitcnt vmcnt(0) lgkmcnt(0)
	v_mfma_f32_16x16x32_bf16 v[174:177], v[178:181], v[190:193], v[174:177]
	v_mfma_f32_16x16x32_bf16 v[162:165], v[194:197], v[190:193], v[162:165]
	v_subrev_u32_e32 v194, s84, v46
	v_lshrrev_b32_e32 v195, 8, v194
	v_lshl_add_u32 v194, v195, 4, v194
	ds_read_b128 v[194:197], v194 offset:8192
	v_lshl_add_u64 v[46:47], v[14:15], 0, v[34:35]
	v_subrev_u32_e32 v178, s84, v46
	v_lshrrev_b32_e32 v179, 8, v178
	v_lshl_add_u32 v178, v179, 4, v178
	ds_read_b128 v[178:181], v178 offset:8192
	v_lshl_add_u64 v[46:47], v[14:15], 0, v[38:39]
	v_mfma_f32_16x16x32_bf16 v[6:9], v[170:173], v[190:193], v[6:9]
	v_subrev_u32_e32 v170, s84, v46
	v_lshrrev_b32_e32 v171, 8, v170
	v_lshl_add_u32 v170, v171, 4, v170
	ds_read_b128 v[170:173], v170 offset:8192
	v_lshl_add_u64 v[46:47], v[14:15], 0, v[40:41]
	v_subrev_u32_e32 v186, s84, v46
	v_lshrrev_b32_e32 v187, 8, v186
	v_lshl_add_u32 v186, v187, 4, v186
	ds_read_b128 v[186:189], v186 offset:8192
	v_lshl_add_u64 v[14:15], v[14:15], 0, v[42:43]
	v_mfma_f32_16x16x32_bf16 v[10:13], v[182:185], v[198:201], v[10:13]
	v_subrev_u32_e32 v182, s84, v14
	v_lshrrev_b32_e32 v183, 8, v182
	v_lshl_add_u32 v182, v183, 4, v182
	ds_read_b128 v[182:185], v182 offset:8192
	v_and_b32_e32 v14, 0xffffff80, v2
	v_ashrrev_i32_e32 v2, 31, v2
	v_and_b32_e32 v2, 0x7fffffff, v2
	v_bitop3_b32 v2, v14, v2, v20 bitop3:0x36
	v_mfma_f32_16x16x32_bf16 v[50:53], v[166:169], v[198:201], v[50:53]
	s_waitcnt vmcnt(0) lgkmcnt(0)
	v_mfma_f32_16x16x32_bf16 v[158:161], v[194:197], v[198:201], v[158:161]
	s_nop 7
	v_ashrrev_i32_e32 v15, 31, v158
	v_and_b32_e32 v14, 0xffffff80, v158
	v_and_b32_e32 v15, 0x7fffffff, v15
	v_bitop3_b32 v14, v14, v15, v56 bitop3:0x36
	v_and_b32_e32 v15, 0xffffff80, v3
	v_ashrrev_i32_e32 v3, 31, v3
	v_and_b32_e32 v3, 0x7fffffff, v3
	v_ashrrev_i32_e32 v18, 31, v159
	v_bitop3_b32 v3, v15, v3, v57 bitop3:0x36
	v_and_b32_e32 v15, 0xffffff80, v159
	v_and_b32_e32 v18, 0x7fffffff, v18
	v_bitop3_b32 v15, v15, v18, v58 bitop3:0x36
	v_and_b32_e32 v18, 0xffffff80, v4
	v_ashrrev_i32_e32 v4, 31, v4
	v_and_b32_e32 v4, 0x7fffffff, v4
	v_ashrrev_i32_e32 v46, 31, v160
	v_bitop3_b32 v4, v18, v4, v59 bitop3:0x36
	v_and_b32_e32 v18, 0xffffff80, v160
	v_and_b32_e32 v46, 0x7fffffff, v46
	v_mfma_f32_16x16x32_bf16 v[162:165], v[170:173], v[198:201], v[162:165]
	v_bitop3_b32 v18, v18, v46, v60 bitop3:0x36
	v_and_b32_e32 v46, 0xffffff80, v5
	v_ashrrev_i32_e32 v5, 31, v5
	v_and_b32_e32 v5, 0x7fffffff, v5
	v_ashrrev_i32_e32 v47, 31, v161
	v_bitop3_b32 v5, v46, v5, v61 bitop3:0x36
	v_and_b32_e32 v46, 0xffffff80, v161
	v_and_b32_e32 v47, 0x7fffffff, v47
	v_bitop3_b32 v46, v46, v47, v62 bitop3:0x36
	v_and_b32_e32 v47, 0xffffff80, v10
	v_ashrrev_i32_e32 v10, 31, v10
	v_and_b32_e32 v10, 0x7fffffff, v10
	v_ashrrev_i32_e32 v48, 31, v162
	v_bitop3_b32 v10, v47, v10, v63 bitop3:0x36
	v_and_b32_e32 v47, 0xffffff80, v162
	v_and_b32_e32 v48, 0x7fffffff, v48
	v_bitop3_b32 v47, v47, v48, v64 bitop3:0x36
	v_and_b32_e32 v48, 0xffffff80, v11
	v_ashrrev_i32_e32 v11, 31, v11
	v_and_b32_e32 v11, 0x7fffffff, v11
	v_ashrrev_i32_e32 v153, 31, v163
	v_bitop3_b32 v11, v48, v11, v65 bitop3:0x36
	v_and_b32_e32 v48, 0xffffff80, v163
	v_and_b32_e32 v153, 0x7fffffff, v153
	v_bitop3_b32 v48, v48, v153, v66 bitop3:0x36
	v_and_b32_e32 v153, 0xffffff80, v12
	v_ashrrev_i32_e32 v12, 31, v12
	v_and_b32_e32 v12, 0x7fffffff, v12
	v_ashrrev_i32_e32 v158, 31, v164
	v_bitop3_b32 v12, v153, v12, v67 bitop3:0x36
	v_and_b32_e32 v153, 0xffffff80, v164
	v_and_b32_e32 v158, 0x7fffffff, v158
	v_mfma_f32_16x16x32_bf16 v[166:169], v[186:189], v[198:201], v[174:177]
	v_bitop3_b32 v153, v153, v158, v68 bitop3:0x36
	v_and_b32_e32 v158, 0xffffff80, v13
	v_ashrrev_i32_e32 v13, 31, v13
	v_and_b32_e32 v13, 0x7fffffff, v13
	v_ashrrev_i32_e32 v159, 31, v165
	v_bitop3_b32 v13, v158, v13, v69 bitop3:0x36
	v_and_b32_e32 v158, 0xffffff80, v165
	v_and_b32_e32 v159, 0x7fffffff, v159
	v_bitop3_b32 v158, v158, v159, v70 bitop3:0x36
	v_and_b32_e32 v159, 0xffffff80, v50
	v_ashrrev_i32_e32 v50, 31, v50
	v_and_b32_e32 v50, 0x7fffffff, v50
	v_ashrrev_i32_e32 v160, 31, v166
	v_bitop3_b32 v50, v159, v50, v71 bitop3:0x36
	v_and_b32_e32 v159, 0xffffff80, v166
	v_and_b32_e32 v160, 0x7fffffff, v160
	v_bitop3_b32 v159, v159, v160, v72 bitop3:0x36
; __device__ __forceinline__ int key_pack(float v, int payload, int mask) {
;   int b = (__float_as_int(v) & ~mask) | payload;
;   return b ^ ((b >> 31) & 0x7fffffff);
; }
; __device__ __forceinline__ void sort16p(int (&v)[16]) {
; #pragma unroll
;   for (int k = 2; k <= 16; k <<= 1)
; #pragma unroll
;     for (int j = k >> 1; j > 0; j >>= 1)
; #pragma unroll
;       for (int i = 0; i < 16; ++i) {
;         int l = i ^ j;
;         if (l > i) {
;           if ((i & k) == 0) { CE1(v[i], v[l]); }
;           else { CE1(v[l], v[i]); }
;         }
;       }
; }
; __device__ void ph_score(const P& p, int* lds) {
;     ...
;       int a[16], b[16];
; #pragma unroll
;       for (int mt = 0; mt < 4; ++mt)
; #pragma unroll
;         for (int r = 0; r < 4; ++r) {
;           a[mt * 4 + r] = key_pack(sc[mt][r], mt * 16 + fq * 4 + r, 0x7f);
;           b[mt * 4 + r] = key_pack(sc[mt + 4][r], (mt + 4) * 16 + fq * 4 + r, 0x7f);
;         }
;       sort16p(a);
;       __builtin_amdgcn_sched_barrier(0);
;       sort16p(b);
	v_and_b32_e32 v160, 0xffffff80, v51
	v_ashrrev_i32_e32 v51, 31, v51
	v_and_b32_e32 v51, 0x7fffffff, v51
	v_ashrrev_i32_e32 v161, 31, v167
	v_bitop3_b32 v51, v160, v51, v73 bitop3:0x36
	v_and_b32_e32 v160, 0xffffff80, v167
	v_and_b32_e32 v161, 0x7fffffff, v161
	v_bitop3_b32 v160, v160, v161, v74 bitop3:0x36
	v_and_b32_e32 v161, 0xffffff80, v52
	v_ashrrev_i32_e32 v52, 31, v52
	v_and_b32_e32 v52, 0x7fffffff, v52
	v_ashrrev_i32_e32 v162, 31, v168
	v_mfma_f32_16x16x32_bf16 v[154:157], v[178:181], v[198:201], v[154:157]
	v_bitop3_b32 v52, v161, v52, v75 bitop3:0x36
	v_and_b32_e32 v161, 0xffffff80, v168
	v_and_b32_e32 v162, 0x7fffffff, v162
	v_bitop3_b32 v161, v161, v162, v76 bitop3:0x36
	v_and_b32_e32 v162, 0xffffff80, v53
	v_ashrrev_i32_e32 v53, 31, v53
	v_mfma_f32_16x16x32_bf16 v[6:9], v[182:185], v[198:201], v[6:9]
	v_and_b32_e32 v53, 0x7fffffff, v53
	v_ashrrev_i32_e32 v163, 31, v169
	v_bitop3_b32 v53, v162, v53, v77 bitop3:0x36
	v_and_b32_e32 v162, 0xffffff80, v169
	v_and_b32_e32 v163, 0x7fffffff, v163
	v_bitop3_b32 v162, v162, v163, v78 bitop3:0x36
	v_and_b32_e32 v163, 0xffffff80, v154
	v_ashrrev_i32_e32 v154, 31, v154
	v_and_b32_e32 v154, 0x7fffffff, v154
	v_bitop3_b32 v154, v163, v154, v79 bitop3:0x36
	v_and_b32_e32 v163, 0xffffff80, v6
	v_ashrrev_i32_e32 v6, 31, v6
	v_and_b32_e32 v6, 0x7fffffff, v6
	v_bitop3_b32 v6, v163, v6, v80 bitop3:0x36
	v_and_b32_e32 v163, 0xffffff80, v155
	v_ashrrev_i32_e32 v155, 31, v155
	v_and_b32_e32 v155, 0x7fffffff, v155
	v_bitop3_b32 v155, v163, v155, v81 bitop3:0x36
	v_and_b32_e32 v163, 0xffffff80, v7
	v_ashrrev_i32_e32 v7, 31, v7
	v_and_b32_e32 v7, 0x7fffffff, v7
	v_bitop3_b32 v7, v163, v7, v82 bitop3:0x36
	v_and_b32_e32 v163, 0xffffff80, v156
	v_ashrrev_i32_e32 v156, 31, v156
	v_and_b32_e32 v156, 0x7fffffff, v156
	v_bitop3_b32 v156, v163, v156, v83 bitop3:0x36
	v_and_b32_e32 v163, 0xffffff80, v8
	v_ashrrev_i32_e32 v8, 31, v8
	v_and_b32_e32 v8, 0x7fffffff, v8
	v_bitop3_b32 v8, v163, v8, v84 bitop3:0x36
	v_and_b32_e32 v163, 0xffffff80, v157
	v_ashrrev_i32_e32 v157, 31, v157
	v_and_b32_e32 v157, 0x7fffffff, v157
	v_bitop3_b32 v157, v163, v157, v85 bitop3:0x36
	v_and_b32_e32 v163, 0xffffff80, v9
	v_ashrrev_i32_e32 v9, 31, v9
	v_and_b32_e32 v9, 0x7fffffff, v9
	v_bitop3_b32 v9, v163, v9, v86 bitop3:0x36
	v_max_i32_e32 v163, v2, v3
	v_min_i32_e32 v2, v2, v3
	v_max_i32_e32 v3, v5, v4
	v_min_i32_e32 v4, v5, v4
	v_max_i32_e32 v5, v10, v11
	v_min_i32_e32 v10, v10, v11
	v_max_i32_e32 v11, v13, v12
	v_min_i32_e32 v12, v13, v12
	v_max_i32_e32 v13, v50, v51
	v_min_i32_e32 v50, v50, v51
	v_max_i32_e32 v51, v53, v52
	v_min_i32_e32 v52, v53, v52
	v_max_i32_e32 v53, v154, v155
	v_min_i32_e32 v154, v154, v155
	v_max_i32_e32 v155, v157, v156
	v_min_i32_e32 v156, v157, v156
	v_max_i32_e32 v157, v163, v4
	v_min_i32_e32 v4, v163, v4
	v_max_i32_e32 v163, v2, v3
	v_min_i32_e32 v2, v2, v3
	v_max_i32_e32 v3, v12, v5
	v_min_i32_e32 v5, v12, v5
	v_max_i32_e32 v12, v11, v10
	v_min_i32_e32 v10, v11, v10
	v_max_i32_e32 v11, v13, v52
	v_min_i32_e32 v13, v13, v52
	v_max_i32_e32 v52, v50, v51
	v_min_i32_e32 v50, v50, v51
	v_max_i32_e32 v51, v156, v53
	v_min_i32_e32 v53, v156, v53
	v_max_i32_e32 v156, v155, v154
	v_min_i32_e32 v154, v155, v154
	v_max_i32_e32 v155, v157, v163
	v_min_i32_e32 v157, v157, v163
	v_max_i32_e32 v163, v4, v2
	v_min_i32_e32 v2, v4, v2
	v_max_i32_e32 v4, v10, v5
	v_min_i32_e32 v5, v10, v5
	v_max_i32_e32 v10, v12, v3
	v_min_i32_e32 v3, v12, v3
	v_max_i32_e32 v12, v11, v52
	v_min_i32_e32 v11, v11, v52
	v_max_i32_e32 v52, v13, v50
	v_min_i32_e32 v13, v13, v50
	v_max_i32_e32 v50, v154, v53
	v_min_i32_e32 v53, v154, v53
	v_max_i32_e32 v154, v156, v51
	v_min_i32_e32 v51, v156, v51
	v_max_i32_e32 v156, v155, v5
	v_min_i32_e32 v5, v155, v5
	v_max_i32_e32 v155, v157, v4
	v_min_i32_e32 v4, v157, v4
	v_max_i32_e32 v157, v163, v3
	v_min_i32_e32 v3, v163, v3
	v_max_i32_e32 v163, v2, v10
	v_min_i32_e32 v2, v2, v10
	v_max_i32_e32 v10, v53, v12
	v_min_i32_e32 v12, v53, v12
	v_max_i32_e32 v53, v50, v11
	v_min_i32_e32 v11, v50, v11
	v_max_i32_e32 v50, v51, v52
	v_min_i32_e32 v51, v51, v52
	v_max_i32_e32 v52, v154, v13
	v_min_i32_e32 v13, v154, v13
	v_max_i32_e32 v154, v156, v157
	v_min_i32_e32 v156, v156, v157
	v_max_i32_e32 v157, v155, v163
	v_min_i32_e32 v155, v155, v163
	v_max_i32_e32 v163, v5, v3
	v_min_i32_e32 v3, v5, v3
	v_max_i32_e32 v5, v4, v2
	v_min_i32_e32 v2, v4, v2
	v_max_i32_e32 v4, v51, v12
	v_min_i32_e32 v12, v51, v12
	v_max_i32_e32 v51, v13, v11
	v_min_i32_e32 v11, v13, v11
	v_max_i32_e32 v13, v50, v10
	v_min_i32_e32 v10, v50, v10
	v_max_i32_e32 v50, v52, v53
	v_min_i32_e32 v52, v52, v53
	v_max_i32_e32 v53, v154, v157
	v_min_i32_e32 v154, v154, v157
	v_max_i32_e32 v157, v156, v155
	v_min_i32_e32 v155, v156, v155
	v_max_i32_e32 v156, v163, v5
	v_min_i32_e32 v5, v163, v5
	v_max_i32_e32 v163, v3, v2
	v_min_i32_e32 v2, v3, v2
	v_max_i32_e32 v3, v11, v12
	v_min_i32_e32 v11, v11, v12
	v_max_i32_e32 v12, v51, v4
	v_min_i32_e32 v4, v51, v4
	v_max_i32_e32 v51, v52, v10
	v_min_i32_e32 v10, v52, v10
	v_max_i32_e32 v52, v50, v13
	v_min_i32_e32 v13, v50, v13
	v_max_i32_e32 v50, v53, v11
	v_min_i32_e32 v11, v53, v11
	v_max_i32_e32 v53, v154, v3
	v_min_i32_e32 v3, v154, v3
	v_max_i32_e32 v154, v157, v4
	v_min_i32_e32 v4, v157, v4
	v_max_i32_e32 v157, v155, v12
	v_min_i32_e32 v12, v155, v12
	v_max_i32_e32 v155, v156, v10
	v_min_i32_e32 v10, v156, v10
	v_max_i32_e32 v156, v5, v51
	v_min_i32_e32 v5, v5, v51
	v_max_i32_e32 v51, v163, v13
	v_min_i32_e32 v13, v163, v13
	v_max_i32_e32 v163, v2, v52
	v_min_i32_e32 v2, v2, v52
	v_max_i32_e32 v52, v50, v155
	v_min_i32_e32 v50, v50, v155
	v_max_i32_e32 v155, v53, v156
	v_min_i32_e32 v53, v53, v156
; __device__ __forceinline__ void sort16p(int (&v)[16]) {
; #pragma unroll
;   for (int k = 2; k <= 16; k <<= 1)
; #pragma unroll
;     for (int j = k >> 1; j > 0; j >>= 1)
; #pragma unroll
;       for (int i = 0; i < 16; ++i) {
;         int l = i ^ j;
;         if (l > i) {
;           if ((i & k) == 0) { CE1(v[i], v[l]); }
;           else { CE1(v[l], v[i]); }
;         }
;       }
; }
; __device__ __forceinline__ void merge16p(int (&a)[16], const int (&b)[16]) {
; #pragma unroll
;   for (int i = 0; i < 16; ++i) a[i] = max(a[i], b[15 - i]);
; #pragma unroll
;   for (int j = 8; j > 0; j >>= 1)
; #pragma unroll
;     for (int i = 0; i < 16; ++i) {
;       int l = i ^ j;
;       if (l > i) { CE1(a[i], a[l]); }
;     }
; }
; __device__ void ph_score(const P& p, int* lds) {
;     ...
;       sort16p(a);
;       __builtin_amdgcn_sched_barrier(0);
;       sort16p(b);
;       __builtin_amdgcn_sched_barrier(0);
;       merge16p(a, b);
	v_max_i32_e32 v156, v154, v51
	v_min_i32_e32 v51, v154, v51
	v_max_i32_e32 v154, v157, v163
	v_min_i32_e32 v157, v157, v163
	v_max_i32_e32 v163, v11, v10
	v_min_i32_e32 v10, v11, v10
	v_max_i32_e32 v11, v3, v5
	v_min_i32_e32 v3, v3, v5
	v_max_i32_e32 v5, v4, v13
	v_min_i32_e32 v4, v4, v13
	v_max_i32_e32 v13, v12, v2
	v_min_i32_e32 v2, v12, v2
	v_max_i32_e32 v12, v52, v156
	v_min_i32_e32 v52, v52, v156
	v_max_i32_e32 v156, v155, v154
	v_min_i32_e32 v154, v155, v154
	v_max_i32_e32 v155, v50, v51
	v_min_i32_e32 v50, v50, v51
	v_max_i32_e32 v51, v53, v157
	v_min_i32_e32 v53, v53, v157
	v_max_i32_e32 v157, v163, v5
	v_min_i32_e32 v5, v163, v5
	v_max_i32_e32 v163, v11, v13
	v_min_i32_e32 v11, v11, v13
	v_max_i32_e32 v13, v10, v4
	v_min_i32_e32 v4, v10, v4
	v_max_i32_e32 v10, v3, v2
	v_min_i32_e32 v2, v3, v2
	v_min_i32_e32 v3, v12, v156
	v_min_i32_e32 v164, v52, v154
	v_min_i32_e32 v165, v155, v51
	v_min_i32_e32 v166, v50, v53
	v_min_i32_e32 v167, v157, v163
	v_min_i32_e32 v168, v5, v11
	v_min_i32_e32 v169, v13, v10
	v_min_i32_e32 v170, v4, v2
	v_max_i32_e32 v171, v14, v15
	v_min_i32_e32 v14, v14, v15
	v_max_i32_e32 v15, v46, v18
	v_min_i32_e32 v18, v46, v18
	v_max_i32_e32 v46, v47, v48
	v_min_i32_e32 v47, v47, v48
	v_max_i32_e32 v48, v158, v153
	v_min_i32_e32 v153, v158, v153
	v_max_i32_e32 v158, v159, v160
	v_min_i32_e32 v159, v159, v160
	v_max_i32_e32 v160, v162, v161
	v_min_i32_e32 v161, v162, v161
	v_max_i32_e32 v162, v6, v7
	v_min_i32_e32 v6, v6, v7
	v_max_i32_e32 v7, v9, v8
	v_min_i32_e32 v8, v9, v8
	v_max_i32_e32 v9, v171, v18
	v_min_i32_e32 v18, v171, v18
	v_max_i32_e32 v171, v14, v15
	v_min_i32_e32 v14, v14, v15
	v_max_i32_e32 v15, v153, v46
	v_min_i32_e32 v46, v153, v46
	v_max_i32_e32 v153, v48, v47
	v_min_i32_e32 v47, v48, v47
	v_max_i32_e32 v48, v158, v161
	v_min_i32_e32 v158, v158, v161
	v_max_i32_e32 v161, v159, v160
	v_min_i32_e32 v159, v159, v160
	v_max_i32_e32 v160, v8, v162
	v_min_i32_e32 v8, v8, v162
	v_max_i32_e32 v162, v7, v6
	v_min_i32_e32 v6, v7, v6
	v_max_i32_e32 v7, v9, v171
	v_min_i32_e32 v9, v9, v171
	v_max_i32_e32 v171, v18, v14
	v_min_i32_e32 v14, v18, v14
	v_max_i32_e32 v18, v47, v46
	v_min_i32_e32 v46, v47, v46
	v_max_i32_e32 v47, v153, v15
	v_min_i32_e32 v15, v153, v15
	v_max_i32_e32 v153, v48, v161
	v_min_i32_e32 v48, v48, v161
	v_max_i32_e32 v161, v158, v159
	v_min_i32_e32 v158, v158, v159
	v_max_i32_e32 v159, v6, v8
	v_min_i32_e32 v6, v6, v8
	v_max_i32_e32 v8, v162, v160
	v_min_i32_e32 v160, v162, v160
	v_max_i32_e32 v162, v7, v46
	v_min_i32_e32 v7, v7, v46
	v_max_i32_e32 v46, v9, v18
	v_min_i32_e32 v9, v9, v18
	v_max_i32_e32 v18, v171, v15
	v_min_i32_e32 v15, v171, v15
	v_max_i32_e32 v171, v14, v47
	v_min_i32_e32 v14, v14, v47
	v_max_i32_e32 v47, v6, v153
	v_min_i32_e32 v6, v6, v153
	v_max_i32_e32 v153, v159, v48
	v_min_i32_e32 v48, v159, v48
	v_max_i32_e32 v159, v160, v161
	v_min_i32_e32 v160, v160, v161
	v_max_i32_e32 v161, v8, v158
	v_min_i32_e32 v8, v8, v158
	v_max_i32_e32 v158, v162, v18
	v_min_i32_e32 v18, v162, v18
	v_max_i32_e32 v162, v46, v171
	v_min_i32_e32 v46, v46, v171
	v_max_i32_e32 v171, v7, v15
	v_min_i32_e32 v7, v7, v15
	v_max_i32_e32 v15, v9, v14
	v_min_i32_e32 v9, v9, v14
	v_max_i32_e32 v14, v160, v6
	v_min_i32_e32 v6, v160, v6
	v_max_i32_e32 v160, v8, v48
	v_min_i32_e32 v8, v8, v48
	v_max_i32_e32 v48, v159, v47
	v_min_i32_e32 v47, v159, v47
	v_max_i32_e32 v159, v161, v153
	v_min_i32_e32 v153, v161, v153
	v_max_i32_e32 v161, v158, v162
	v_min_i32_e32 v158, v158, v162
	v_max_i32_e32 v162, v18, v46
	v_min_i32_e32 v18, v18, v46
	v_max_i32_e32 v46, v171, v15
	v_min_i32_e32 v15, v171, v15
	v_max_i32_e32 v171, v7, v9
	v_min_i32_e32 v7, v7, v9
	v_max_i32_e32 v9, v8, v6
	v_min_i32_e32 v6, v8, v6
	v_max_i32_e32 v8, v160, v14
	v_min_i32_e32 v14, v160, v14
	v_max_i32_e32 v160, v153, v47
	v_min_i32_e32 v47, v153, v47
	v_max_i32_e32 v153, v159, v48
	v_min_i32_e32 v48, v159, v48
	v_max_i32_e32 v159, v161, v6
	v_min_i32_e32 v6, v161, v6
	v_max_i32_e32 v161, v158, v9
	v_min_i32_e32 v9, v158, v9
	v_max_i32_e32 v158, v162, v14
	v_min_i32_e32 v14, v162, v14
	v_max_i32_e32 v162, v18, v8
	v_min_i32_e32 v8, v18, v8
	v_max_i32_e32 v18, v46, v47
	v_min_i32_e32 v46, v46, v47
	v_max_i32_e32 v47, v15, v160
	v_min_i32_e32 v15, v15, v160
	v_max_i32_e32 v160, v171, v48
	v_min_i32_e32 v48, v171, v48
	v_max_i32_e32 v171, v7, v153
	v_min_i32_e32 v7, v7, v153
	v_max_i32_e32 v153, v159, v18
	v_min_i32_e32 v18, v159, v18
	v_max_i32_e32 v159, v161, v47
	v_min_i32_e32 v47, v161, v47
	v_max_i32_e32 v161, v158, v160
	v_min_i32_e32 v158, v158, v160
	v_max_i32_e32 v160, v162, v171
	v_min_i32_e32 v162, v162, v171
	v_max_i32_e32 v171, v6, v46
	v_min_i32_e32 v6, v6, v46
	v_max_i32_e32 v46, v9, v15
	v_min_i32_e32 v9, v9, v15
	v_max_i32_e32 v15, v14, v48
	v_min_i32_e32 v14, v14, v48
	v_max_i32_e32 v48, v8, v7
	v_min_i32_e32 v7, v8, v7
	v_max_i32_e32 v8, v153, v161
	v_min_i32_e32 v153, v153, v161
	v_max_i32_e32 v161, v159, v160
	v_min_i32_e32 v159, v159, v160
	v_max_i32_e32 v160, v18, v158
	v_min_i32_e32 v18, v18, v158
	v_max_i32_e32 v158, v47, v162
	v_min_i32_e32 v47, v47, v162
	v_max_i32_e32 v162, v171, v15
	v_min_i32_e32 v15, v171, v15
	v_max_i32_e32 v171, v46, v48
	v_min_i32_e32 v46, v46, v48
	v_max_i32_e32 v48, v6, v14
	v_min_i32_e32 v6, v6, v14
	v_max_i32_e32 v14, v9, v7
	v_min_i32_e32 v7, v9, v7
	v_min_i32_e32 v9, v8, v161
	v_min_i32_e32 v172, v153, v159
	v_min_i32_e32 v173, v160, v158
	v_min_i32_e32 v174, v18, v47
	v_min_i32_e32 v175, v162, v171
	v_min_i32_e32 v176, v15, v46
	v_min_i32_e32 v177, v48, v14
	v_min_i32_e32 v178, v6, v7
	v_max3_i32 v12, v12, v156, v178
	v_max3_i32 v3, v3, v6, v7
	v_max3_i32 v6, v52, v154, v177
; __device__ __forceinline__ void merge16p(int (&a)[16], const int (&b)[16]) {
; #pragma unroll
;   for (int i = 0; i < 16; ++i) a[i] = max(a[i], b[15 - i]);
; #pragma unroll
;   for (int j = 8; j > 0; j >>= 1)
; #pragma unroll
;     for (int i = 0; i < 16; ++i) {
;       int l = i ^ j;
;       if (l > i) { CE1(a[i], a[l]); }
;     }
; }
; __device__ __forceinline__ void xmerge16p(int (&a)[16], int mask) {
;   int b[16];
; #pragma unroll
;   for (int i = 0; i < 16; ++i) b[i] = (mask == 16) ? __builtin_amdgcn_ds_swizzle(a[i], 0x401F) : __shfl_xor(a[i], 32);
;   merge16p(a, b);
; }
; __device__ void ph_score(const P& p, int* lds) {
;     ...
;       xmerge16p(a, 16); xmerge16p(a, 32);
	v_max3_i32 v7, v164, v48, v14
	v_max3_i32 v14, v155, v51, v176
	v_max3_i32 v15, v165, v15, v46
	v_max3_i32 v46, v50, v53, v175
	v_max3_i32 v48, v166, v162, v171
	v_max3_i32 v50, v157, v163, v174
	v_max3_i32 v18, v167, v18, v47
	v_max3_i32 v5, v5, v11, v173
	v_max3_i32 v11, v168, v160, v158
	v_max3_i32 v10, v13, v10, v172
	v_max3_i32 v13, v169, v153, v159
	v_max3_i32 v2, v4, v2, v9
	v_max3_i32 v4, v170, v8, v161
	v_max_i32_e32 v8, v12, v50
	v_min_i32_e32 v9, v12, v50
	v_max_i32_e32 v12, v3, v18
	v_min_i32_e32 v3, v3, v18
	v_max_i32_e32 v18, v6, v5
	v_min_i32_e32 v5, v6, v5
	v_max_i32_e32 v6, v7, v11
	v_min_i32_e32 v7, v7, v11
	v_max_i32_e32 v11, v14, v10
	v_min_i32_e32 v10, v14, v10
	v_max_i32_e32 v14, v15, v13
	v_min_i32_e32 v13, v15, v13
	v_max_i32_e32 v15, v46, v2
	v_min_i32_e32 v2, v46, v2
	v_max_i32_e32 v46, v48, v4
	v_min_i32_e32 v4, v48, v4
	v_max_i32_e32 v47, v8, v11
	v_min_i32_e32 v8, v8, v11
	v_max_i32_e32 v11, v12, v14
	v_min_i32_e32 v12, v12, v14
	v_max_i32_e32 v14, v18, v15
	v_min_i32_e32 v15, v18, v15
	v_max_i32_e32 v18, v6, v46
	v_min_i32_e32 v6, v6, v46
	v_max_i32_e32 v46, v9, v10
	v_min_i32_e32 v9, v9, v10
	v_max_i32_e32 v10, v3, v13
	v_min_i32_e32 v3, v3, v13
	v_max_i32_e32 v13, v5, v2
	v_min_i32_e32 v2, v5, v2
	v_max_i32_e32 v5, v7, v4
	v_min_i32_e32 v4, v7, v4
	v_max_i32_e32 v7, v47, v14
	v_min_i32_e32 v14, v47, v14
	v_max_i32_e32 v47, v11, v18
	v_min_i32_e32 v11, v11, v18
	v_max_i32_e32 v18, v8, v15
	v_min_i32_e32 v8, v8, v15
	v_max_i32_e32 v15, v12, v6
	v_min_i32_e32 v6, v12, v6
	v_max_i32_e32 v12, v46, v13
	v_min_i32_e32 v13, v46, v13
	v_max_i32_e32 v46, v10, v5
	v_min_i32_e32 v5, v10, v5
	v_max_i32_e32 v10, v9, v2
	v_min_i32_e32 v2, v9, v2
	v_max_i32_e32 v9, v3, v4
	v_min_i32_e32 v3, v3, v4
	v_max_i32_e32 v4, v7, v47
	v_min_i32_e32 v7, v7, v47
	v_max_i32_e32 v47, v14, v11
	v_min_i32_e32 v11, v14, v11
	v_max_i32_e32 v14, v18, v15
	v_min_i32_e32 v15, v18, v15
	v_max_i32_e32 v18, v8, v6
	v_min_i32_e32 v6, v8, v6
	v_max_i32_e32 v8, v12, v46
	v_min_i32_e32 v12, v12, v46
	v_max_i32_e32 v46, v13, v5
	v_min_i32_e32 v5, v13, v5
	v_max_i32_e32 v13, v10, v9
	v_min_i32_e32 v9, v10, v9
	v_max_i32_e32 v10, v2, v3
	v_min_i32_e32 v2, v2, v3
	ds_swizzle_b32 v3, v4 offset:swizzle(SWAP,16)
	ds_swizzle_b32 v48, v7 offset:swizzle(SWAP,16)
	ds_swizzle_b32 v50, v47 offset:swizzle(SWAP,16)
	ds_swizzle_b32 v51, v11 offset:swizzle(SWAP,16)
	ds_swizzle_b32 v52, v14 offset:swizzle(SWAP,16)
	ds_swizzle_b32 v53, v15 offset:swizzle(SWAP,16)
	ds_swizzle_b32 v153, v18 offset:swizzle(SWAP,16)
	ds_swizzle_b32 v154, v6 offset:swizzle(SWAP,16)
	ds_swizzle_b32 v155, v8 offset:swizzle(SWAP,16)
	ds_swizzle_b32 v156, v12 offset:swizzle(SWAP,16)
	ds_swizzle_b32 v157, v46 offset:swizzle(SWAP,16)
	ds_swizzle_b32 v158, v2 offset:swizzle(SWAP,16)
	ds_swizzle_b32 v159, v10 offset:swizzle(SWAP,16)
	ds_swizzle_b32 v160, v9 offset:swizzle(SWAP,16)
	ds_swizzle_b32 v161, v13 offset:swizzle(SWAP,16)
	ds_swizzle_b32 v162, v5 offset:swizzle(SWAP,16)
	s_waitcnt lgkmcnt(0)
	v_max_i32_e32 v4, v4, v158
	v_max_i32_e32 v7, v7, v159
	v_max_i32_e32 v47, v47, v160
	v_max_i32_e32 v11, v11, v161
	v_max_i32_e32 v14, v14, v162
	v_max_i32_e32 v15, v15, v157
	v_max_i32_e32 v18, v18, v156
	v_max_i32_e32 v6, v6, v155
	v_max_i32_e32 v8, v8, v154
	v_max_i32_e32 v12, v12, v153
	v_max_i32_e32 v46, v46, v53
	v_max_i32_e32 v5, v5, v52
	v_max_i32_e32 v13, v13, v51
	v_max_i32_e32 v9, v9, v50
	v_max_i32_e32 v10, v10, v48
	v_max_i32_e32 v2, v2, v3
	v_max_i32_e32 v3, v4, v8
	v_min_i32_e32 v4, v4, v8
	v_max_i32_e32 v8, v7, v12
	v_min_i32_e32 v7, v7, v12
	v_max_i32_e32 v12, v47, v46
	v_min_i32_e32 v46, v47, v46
	v_max_i32_e32 v47, v11, v5
	v_min_i32_e32 v5, v11, v5
	v_max_i32_e32 v11, v14, v13
	v_min_i32_e32 v13, v14, v13
	v_max_i32_e32 v14, v15, v9
	v_min_i32_e32 v9, v15, v9
	v_max_i32_e32 v15, v18, v10
	v_min_i32_e32 v10, v18, v10
	v_max_i32_e32 v18, v6, v2
	v_min_i32_e32 v2, v6, v2
	v_max_i32_e32 v6, v3, v11
	v_min_i32_e32 v3, v3, v11
	v_max_i32_e32 v11, v8, v14
	v_min_i32_e32 v8, v8, v14
	v_max_i32_e32 v14, v12, v15
	v_min_i32_e32 v12, v12, v15
	v_max_i32_e32 v15, v47, v18
	v_min_i32_e32 v18, v47, v18
	v_max_i32_e32 v47, v4, v13
	v_min_i32_e32 v4, v4, v13
	v_max_i32_e32 v13, v7, v9
	v_min_i32_e32 v7, v7, v9
	v_max_i32_e32 v9, v46, v10
	v_min_i32_e32 v10, v46, v10
	v_max_i32_e32 v46, v5, v2
	v_min_i32_e32 v2, v5, v2
	v_max_i32_e32 v5, v6, v14
	v_min_i32_e32 v6, v6, v14
	v_max_i32_e32 v14, v11, v15
	v_min_i32_e32 v11, v11, v15
	v_max_i32_e32 v15, v3, v12
	v_min_i32_e32 v3, v3, v12
	v_max_i32_e32 v12, v8, v18
	v_min_i32_e32 v8, v8, v18
	v_max_i32_e32 v18, v47, v9
	v_min_i32_e32 v9, v47, v9
	v_max_i32_e32 v47, v13, v46
	v_min_i32_e32 v13, v13, v46
	v_max_i32_e32 v46, v4, v10
	v_min_i32_e32 v4, v4, v10
	v_max_i32_e32 v10, v7, v2
	v_min_i32_e32 v2, v7, v2
	v_max_i32_e32 v7, v5, v14
	v_min_i32_e32 v5, v5, v14
	v_max_i32_e32 v14, v6, v11
	v_min_i32_e32 v6, v6, v11
	v_max_i32_e32 v11, v15, v12
	v_min_i32_e32 v12, v15, v12
	v_max_i32_e32 v15, v3, v8
	v_min_i32_e32 v3, v3, v8
	v_max_i32_e32 v8, v18, v47
	v_min_i32_e32 v18, v18, v47
	v_max_i32_e32 v47, v9, v13
	v_min_i32_e32 v9, v9, v13
	v_max_i32_e32 v13, v46, v10
	v_min_i32_e32 v10, v46, v10
	v_max_i32_e32 v46, v4, v2
	v_min_i32_e32 v2, v4, v2
	ds_bpermute_b32 v4, v54, v7
	ds_bpermute_b32 v48, v54, v5
	ds_bpermute_b32 v50, v54, v14
	ds_bpermute_b32 v51, v54, v6
	ds_bpermute_b32 v52, v54, v11
	ds_bpermute_b32 v53, v54, v12
	ds_bpermute_b32 v153, v54, v15
	ds_bpermute_b32 v154, v54, v3
	ds_bpermute_b32 v155, v54, v8
	ds_bpermute_b32 v156, v54, v18
	ds_bpermute_b32 v157, v54, v47
	ds_bpermute_b32 v158, v54, v2
	ds_bpermute_b32 v159, v54, v46
	ds_bpermute_b32 v160, v54, v10
	ds_bpermute_b32 v161, v54, v13
	ds_bpermute_b32 v162, v54, v9
	s_waitcnt lgkmcnt(4)
; __device__ __forceinline__ f32x4 mfma16(bf16x8 a, bf16x8 b, f32x4 c) { return __builtin_amdgcn_mfma_f32_16x16x32_bf16(a, b, c, 0, 0, 0); }
; __device__ void ph_score(const P& p, int* lds) {
;     ...
;       for (int ks = 0; ks < 4; ++ks) {
;         bf16x8 qf = *(const bf16x8*)(Qb + tok * 2048 + h * 256 + half * 128 + ks * 32 + fq * 8);
; #pragma unroll
;         for (int mt = 0; mt < 8; ++mt) {
;           bf16x8 kf = *(const bf16x8*)(Kb + (mt * 16 + fr) * 128 + ks * 32 + fq * 8);
;           sc[mt] = mfma16(kf, qf, sc[mt]);
;         }
;     ...
;       xmerge16p(a, 16); xmerge16p(a, 32);
;       __builtin_amdgcn_sched_barrier(0);
;       int idx4[4];
; #pragma unroll
;       for (int i = 0; i < 16; ++i) {
;         const int k = key_unmap(a[i]);
;         tv[half][i] = __int_as_float(k & ~0x7f);
;         if ((i >> 2) == 0) idx4[i & 3] = k & 0x7f;
;       }
; #pragma unroll
;       for (int i = 4; i < 16; ++i) {
;         const int k = key_unmap(a[i]) & 0x7f;
;         if ((i >> 2) == 1) idx4[i & 3] = (fq == 1) ? k : idx4[i & 3];
;         if ((i >> 2) == 2) idx4[i & 3] = (fq == 2) ? k : idx4[i & 3];
;         if ((i >> 2) == 3) idx4[i & 3] = (fq == 3) ? k : idx4[i & 3];
;       }
;       *(int4*)(myl + half * 16 + fq * 4) = make_int4(idx4[0], idx4[1], idx4[2], idx4[3]);
	v_max_i32_e32 v7, v7, v158
	s_waitcnt lgkmcnt(3)
	v_max_i32_e32 v5, v5, v159
	s_waitcnt lgkmcnt(2)
	v_max_i32_e32 v14, v14, v160
	s_waitcnt lgkmcnt(1)
	v_max_i32_e32 v6, v6, v161
	s_waitcnt lgkmcnt(0)
	v_max_i32_e32 v11, v11, v162
	v_max_i32_e32 v12, v12, v157
	v_max_i32_e32 v15, v15, v156
	v_max_i32_e32 v3, v3, v155
	v_max_i32_e32 v8, v8, v154
	v_max_i32_e32 v18, v18, v153
	v_max_i32_e32 v47, v47, v53
	v_max_i32_e32 v9, v9, v52
	v_max_i32_e32 v13, v13, v51
	v_max_i32_e32 v10, v10, v50
	v_max_i32_e32 v46, v46, v48
	v_max_i32_e32 v2, v2, v4
	v_max_i32_e32 v4, v7, v8
	v_min_i32_e32 v7, v7, v8
	v_max_i32_e32 v8, v5, v18
	v_min_i32_e32 v5, v5, v18
	v_max_i32_e32 v18, v14, v47
	v_min_i32_e32 v14, v14, v47
	v_max_i32_e32 v47, v6, v9
	v_min_i32_e32 v6, v6, v9
	v_max_i32_e32 v9, v11, v13
	v_min_i32_e32 v11, v11, v13
	v_max_i32_e32 v13, v12, v10
	v_min_i32_e32 v10, v12, v10
	v_max_i32_e32 v12, v15, v46
	v_min_i32_e32 v15, v15, v46
	v_max_i32_e32 v46, v3, v2
	v_min_i32_e32 v2, v3, v2
	v_max_i32_e32 v3, v4, v9
	v_min_i32_e32 v4, v4, v9
	v_max_i32_e32 v9, v8, v13
	v_min_i32_e32 v8, v8, v13
	v_max_i32_e32 v13, v18, v12
	v_min_i32_e32 v12, v18, v12
	v_max_i32_e32 v18, v47, v46
	v_min_i32_e32 v46, v47, v46
	v_max_i32_e32 v47, v7, v11
	v_min_i32_e32 v7, v7, v11
	v_max_i32_e32 v11, v5, v10
	v_min_i32_e32 v5, v5, v10
	v_max_i32_e32 v10, v14, v15
	v_min_i32_e32 v14, v14, v15
	v_max_i32_e32 v15, v6, v2
	v_min_i32_e32 v2, v6, v2
	v_max_i32_e32 v6, v3, v13
	v_min_i32_e32 v3, v3, v13
	v_max_i32_e32 v13, v9, v18
	v_min_i32_e32 v9, v9, v18
	v_max_i32_e32 v48, v4, v12
	v_min_i32_e32 v4, v4, v12
	v_max_i32_e32 v12, v8, v46
	v_min_i32_e32 v8, v8, v46
	v_max_i32_e32 v50, v47, v10
	v_min_i32_e32 v10, v47, v10
	v_max_i32_e32 v47, v11, v15
	v_min_i32_e32 v11, v11, v15
	v_max_i32_e32 v15, v7, v14
	v_min_i32_e32 v7, v7, v14
	v_max_i32_e32 v14, v5, v2
	v_min_i32_e32 v2, v5, v2
	v_max_i32_e32 v5, v6, v13
	v_min_i32_e32 v6, v6, v13
	v_max_i32_e32 v13, v3, v9
	v_min_i32_e32 v3, v3, v9
	v_max_i32_e32 v18, v48, v12
	v_min_i32_e32 v155, v48, v12
	v_max_i32_e32 v52, v4, v8
	v_min_i32_e32 v46, v4, v8
	v_max_i32_e32 v159, v50, v47
	v_min_i32_e32 v156, v50, v47
	v_max_i32_e32 v53, v10, v11
	v_min_i32_e32 v47, v10, v11
	v_max_i32_e32 v160, v15, v14
	v_min_i32_e32 v158, v15, v14
	v_max_i32_e32 v154, v7, v2
	v_min_i32_e32 v51, v7, v2
	v_ashrrev_i32_e32 v2, 31, v5
	v_and_b32_e32 v4, 0x7fffffff, v2
	v_bitop3_b32 v161, v2, v5, s75 bitop3:0x6c
	v_bitop3_b32 v2, v4, s80, v5 bitop3:0x48
	v_ashrrev_i32_e32 v4, 31, v6
	v_and_b32_e32 v5, 0x7fffffff, v4
	v_bitop3_b32 v157, v4, v6, s75 bitop3:0x6c
	v_bitop3_b32 v4, v5, s80, v6 bitop3:0x48
	v_ashrrev_i32_e32 v5, 31, v13
	v_and_b32_e32 v6, 0x7fffffff, v5
	v_bitop3_b32 v153, v5, v13, s75 bitop3:0x6c
	v_bitop3_b32 v5, v6, s80, v13 bitop3:0x48
	v_ashrrev_i32_e32 v6, 31, v3
	v_and_b32_e32 v7, 0x7fffffff, v6
	v_bitop3_b32 v50, v6, v3, s75 bitop3:0x6c
	v_ashrrev_i32_e32 v6, 31, v18
	v_bitop3_b32 v6, v6, s80, v18 bitop3:0x48
	v_cndmask_b32_e64 v2, v2, v6, s[6:7]
	v_ashrrev_i32_e32 v6, 31, v155
	v_bitop3_b32 v6, v6, s80, v155 bitop3:0x48
	v_cndmask_b32_e64 v4, v4, v6, s[6:7]
	v_ashrrev_i32_e32 v6, 31, v52
	v_bitop3_b32 v6, v6, s80, v52 bitop3:0x48
	v_cndmask_b32_e64 v5, v5, v6, s[6:7]
	v_ashrrev_i32_e32 v6, 31, v46
	v_bitop3_b32 v3, v7, s80, v3 bitop3:0x48
	v_bitop3_b32 v6, v6, s80, v46 bitop3:0x48
	v_cndmask_b32_e64 v3, v3, v6, s[6:7]
	v_ashrrev_i32_e32 v6, 31, v159
	v_bitop3_b32 v6, v6, s80, v159 bitop3:0x48
	v_cndmask_b32_e64 v2, v2, v6, s[4:5]
	v_ashrrev_i32_e32 v6, 31, v156
	v_bitop3_b32 v6, v6, s80, v156 bitop3:0x48
	v_cndmask_b32_e64 v4, v4, v6, s[4:5]
	v_ashrrev_i32_e32 v6, 31, v53
	v_bitop3_b32 v6, v6, s80, v53 bitop3:0x48
	v_cndmask_b32_e64 v5, v5, v6, s[4:5]
	v_ashrrev_i32_e32 v6, 31, v47
	v_bitop3_b32 v6, v6, s80, v47 bitop3:0x48
	v_cndmask_b32_e64 v6, v3, v6, s[4:5]
	v_ashrrev_i32_e32 v3, 31, v160
	v_bitop3_b32 v3, v3, s80, v160 bitop3:0x48
	v_cndmask_b32_e64 v2, v2, v3, s[0:1]
	v_ashrrev_i32_e32 v3, 31, v158
	v_bitop3_b32 v3, v3, s80, v158 bitop3:0x48
	v_cndmask_b32_e64 v3, v4, v3, s[0:1]
	v_ashrrev_i32_e32 v4, 31, v154
	v_bitop3_b32 v4, v4, s80, v154 bitop3:0x48
	v_cndmask_b32_e64 v4, v5, v4, s[0:1]
	v_ashrrev_i32_e32 v5, 31, v51
	v_bitop3_b32 v5, v5, s80, v51 bitop3:0x48
	v_lshl_add_u64 v[14:15], v[24:25], 0, s[70:71]
	v_cndmask_b32_e64 v5, v6, v5, s[0:1]
	v_lshl_add_u64 v[190:191], v[14:15], 0, v[28:29]
	v_lshl_add_u64 v[10:11], v[14:15], 0, v[30:31]
	v_lshl_add_u64 v[162:163], v[14:15], 0, v[32:33]
	v_lshl_add_u64 v[166:167], v[14:15], 0, v[34:35]
	v_lshl_add_u64 v[170:171], v[14:15], 0, v[36:37]
	v_lshl_add_u64 v[174:175], v[14:15], 0, v[38:39]
	v_lshl_add_u64 v[178:179], v[14:15], 0, v[40:41]
	v_lshl_add_u64 v[182:183], v[14:15], 0, v[42:43]
	ds_write_b128 v150, v[2:5]
	global_load_dwordx4 v[2:5], v[0:1], off offset:256
	v_subrev_u32_e32 v6, s85, v190
	v_lshrrev_b32_e32 v7, 8, v6
	v_lshl_add_u32 v6, v7, 4, v6
	ds_read_b128 v[6:9], v6 offset:43216
	v_lshl_add_u64 v[192:193], v[14:15], 0, 64
	v_subrev_u32_e32 v10, s85, v10
	v_lshrrev_b32_e32 v11, 8, v10
	v_lshl_add_u32 v10, v11, 4, v10
	ds_read_b128 v[10:13], v10 offset:43216
	v_lshl_add_u64 v[194:195], v[14:15], 0, s[76:77]
	v_subrev_u32_e32 v162, s85, v162
	v_lshrrev_b32_e32 v163, 8, v162
	v_lshl_add_u32 v162, v163, 4, v162
	ds_read_b128 v[162:165], v162 offset:43216
	v_cmp_gt_i32_e64 s[26:27], 0, v18
	v_subrev_u32_e32 v166, s85, v166
	v_lshrrev_b32_e32 v167, 8, v166
	v_lshl_add_u32 v166, v167, 4, v166
	ds_read_b128 v[166:169], v166 offset:43216
	v_cmp_gt_i32_e64 s[20:21], 0, v155
	v_subrev_u32_e32 v170, s85, v170
	v_lshrrev_b32_e32 v171, 8, v170
	v_lshl_add_u32 v170, v171, 4, v170
	ds_read_b128 v[170:173], v170 offset:43216
	v_cmp_gt_i32_e64 s[14:15], 0, v52
	v_subrev_u32_e32 v174, s85, v174
	v_lshrrev_b32_e32 v175, 8, v174
	v_lshl_add_u32 v174, v175, 4, v174
	ds_read_b128 v[174:177], v174 offset:43216
	v_cmp_gt_i32_e32 vcc, 0, v46
	v_subrev_u32_e32 v178, s85, v178
	v_lshrrev_b32_e32 v179, 8, v178
	v_lshl_add_u32 v178, v179, 4, v178
	ds_read_b128 v[178:181], v178 offset:43216
	v_cmp_gt_i32_e64 s[28:29], 0, v159
	v_subrev_u32_e32 v182, s85, v182
	v_lshrrev_b32_e32 v183, 8, v182
	v_lshl_add_u32 v182, v183, 4, v182
	ds_read_b128 v[182:185], v182 offset:43216
	v_cmp_gt_i32_e64 s[22:23], 0, v156
	v_cmp_gt_i32_e64 s[16:17], 0, v53
	v_cmp_gt_i32_e64 s[10:11], 0, v47
	v_cmp_gt_i32_e64 s[30:31], 0, v160
	v_cmp_gt_i32_e64 s[24:25], 0, v158
	v_cmp_gt_i32_e64 s[18:19], 0, v154
	v_cmp_gt_i32_e64 s[12:13], 0, v51
	s_waitcnt vmcnt(0) lgkmcnt(0)
; __device__ __forceinline__ f32x4 mfma16(bf16x8 a, bf16x8 b, f32x4 c) { return __builtin_amdgcn_mfma_f32_16x16x32_bf16(a, b, c, 0, 0, 0); }
; __device__ void ph_score(const P& p, int* lds) {
;     ...
;       for (int ks = 0; ks < 4; ++ks) {
;         bf16x8 qf = *(const bf16x8*)(Qb + tok * 2048 + h * 256 + half * 128 + ks * 32 + fq * 8);
; #pragma unroll
;         for (int mt = 0; mt < 8; ++mt) {
;           bf16x8 kf = *(const bf16x8*)(Kb + (mt * 16 + fr) * 128 + ks * 32 + fq * 8);
;           sc[mt] = mfma16(kf, qf, sc[mt]);
;         }
;       }
	v_mfma_f32_16x16x32_bf16 v[162:165], v[162:165], v[2:5], 0
	v_subrev_u32_e32 v186, s85, v190
	v_lshrrev_b32_e32 v187, 8, v186
	v_lshl_add_u32 v186, v187, 4, v186
	ds_read_b128 v[186:189], v186 offset:43280
	v_mfma_f32_16x16x32_bf16 v[6:9], v[6:9], v[2:5], 0
	v_mfma_f32_16x16x32_bf16 v[10:13], v[10:13], v[2:5], 0
	s_waitcnt vmcnt(0) lgkmcnt(0)
	v_mfma_f32_16x16x32_bf16 v[166:169], v[166:169], v[2:5], 0
	s_waitcnt vmcnt(0) lgkmcnt(0)
	v_mfma_f32_16x16x32_bf16 v[170:173], v[170:173], v[2:5], 0
	s_waitcnt vmcnt(0) lgkmcnt(0)
	v_mfma_f32_16x16x32_bf16 v[174:177], v[174:177], v[2:5], 0
	s_waitcnt vmcnt(0) lgkmcnt(0)
	v_mfma_f32_16x16x32_bf16 v[178:181], v[178:181], v[2:5], 0
	s_waitcnt vmcnt(0) lgkmcnt(0)
	v_mfma_f32_16x16x32_bf16 v[2:5], v[182:185], v[2:5], 0
	global_load_dwordx4 v[182:185], v[0:1], off offset:320
	s_waitcnt vmcnt(0) lgkmcnt(0)
	v_mfma_f32_16x16x32_bf16 v[6:9], v[186:189], v[182:185], v[6:9]
	v_lshl_add_u64 v[186:187], v[192:193], 0, v[30:31]
	v_subrev_u32_e32 v186, s85, v186
	v_lshrrev_b32_e32 v187, 8, v186
	v_lshl_add_u32 v186, v187, 4, v186
	ds_read_b128 v[186:189], v186 offset:43216
	s_waitcnt vmcnt(0) lgkmcnt(0)
	v_mfma_f32_16x16x32_bf16 v[10:13], v[186:189], v[182:185], v[10:13]
	v_lshl_add_u64 v[186:187], v[192:193], 0, v[32:33]
	v_subrev_u32_e32 v186, s85, v186
	v_lshrrev_b32_e32 v187, 8, v186
	v_lshl_add_u32 v186, v187, 4, v186
	ds_read_b128 v[186:189], v186 offset:43216
	s_waitcnt vmcnt(0) lgkmcnt(0)
	v_mfma_f32_16x16x32_bf16 v[162:165], v[186:189], v[182:185], v[162:165]
	v_lshl_add_u64 v[186:187], v[192:193], 0, v[34:35]
	v_subrev_u32_e32 v186, s85, v186
	v_lshrrev_b32_e32 v187, 8, v186
	v_lshl_add_u32 v186, v187, 4, v186
	ds_read_b128 v[186:189], v186 offset:43216
	s_waitcnt vmcnt(0) lgkmcnt(0)
	v_mfma_f32_16x16x32_bf16 v[166:169], v[186:189], v[182:185], v[166:169]
	v_lshl_add_u64 v[186:187], v[192:193], 0, v[36:37]
	v_subrev_u32_e32 v186, s85, v186
	v_lshrrev_b32_e32 v187, 8, v186
	v_lshl_add_u32 v186, v187, 4, v186
	ds_read_b128 v[186:189], v186 offset:43216
	s_waitcnt vmcnt(0) lgkmcnt(0)
	v_mfma_f32_16x16x32_bf16 v[170:173], v[186:189], v[182:185], v[170:173]
	v_lshl_add_u64 v[186:187], v[192:193], 0, v[38:39]
	v_subrev_u32_e32 v186, s85, v186
	v_lshrrev_b32_e32 v187, 8, v186
	v_lshl_add_u32 v186, v187, 4, v186
	ds_read_b128 v[186:189], v186 offset:43216
	s_waitcnt vmcnt(0) lgkmcnt(0)
	v_mfma_f32_16x16x32_bf16 v[174:177], v[186:189], v[182:185], v[174:177]
	v_lshl_add_u64 v[186:187], v[192:193], 0, v[40:41]
	v_subrev_u32_e32 v186, s85, v186
	v_lshrrev_b32_e32 v187, 8, v186
	v_lshl_add_u32 v186, v187, 4, v186
	ds_read_b128 v[186:189], v186 offset:43216
	s_waitcnt vmcnt(0) lgkmcnt(0)
	v_mfma_f32_16x16x32_bf16 v[178:181], v[186:189], v[182:185], v[178:181]
	v_lshl_add_u64 v[186:187], v[192:193], 0, v[42:43]
	v_subrev_u32_e32 v186, s85, v186
	v_lshrrev_b32_e32 v187, 8, v186
	v_lshl_add_u32 v186, v187, 4, v186
	ds_read_b128 v[186:189], v186 offset:43216
	v_lshl_add_u64 v[192:193], v[14:15], 0, s[72:73]
	s_waitcnt vmcnt(0) lgkmcnt(0)
	v_mfma_f32_16x16x32_bf16 v[2:5], v[186:189], v[182:185], v[2:5]
	global_load_dwordx4 v[182:185], v[0:1], off offset:384
	v_subrev_u32_e32 v186, s85, v190
	v_lshrrev_b32_e32 v187, 8, v186
	v_lshl_add_u32 v186, v187, 4, v186
	ds_read_b128 v[186:189], v186 offset:43344
	s_waitcnt vmcnt(0) lgkmcnt(0)
	v_mfma_f32_16x16x32_bf16 v[6:9], v[186:189], v[182:185], v[6:9]
	v_lshl_add_u64 v[186:187], v[192:193], 0, v[30:31]
	v_subrev_u32_e32 v186, s85, v186
	v_lshrrev_b32_e32 v187, 8, v186
	v_lshl_add_u32 v186, v187, 4, v186
	ds_read_b128 v[186:189], v186 offset:43216
	s_waitcnt vmcnt(0) lgkmcnt(0)
	v_mfma_f32_16x16x32_bf16 v[10:13], v[186:189], v[182:185], v[10:13]
	v_lshl_add_u64 v[186:187], v[192:193], 0, v[32:33]
	v_subrev_u32_e32 v186, s85, v186
	v_lshrrev_b32_e32 v187, 8, v186
	v_lshl_add_u32 v186, v187, 4, v186
	ds_read_b128 v[186:189], v186 offset:43216
	s_waitcnt vmcnt(0) lgkmcnt(0)
	v_mfma_f32_16x16x32_bf16 v[162:165], v[186:189], v[182:185], v[162:165]
	v_lshl_add_u64 v[186:187], v[192:193], 0, v[34:35]
	v_subrev_u32_e32 v186, s85, v186
	v_lshrrev_b32_e32 v187, 8, v186
	v_lshl_add_u32 v186, v187, 4, v186
	ds_read_b128 v[186:189], v186 offset:43216
	s_waitcnt vmcnt(0) lgkmcnt(0)
	v_mfma_f32_16x16x32_bf16 v[166:169], v[186:189], v[182:185], v[166:169]
	v_lshl_add_u64 v[186:187], v[192:193], 0, v[36:37]
	v_subrev_u32_e32 v186, s85, v186
	v_lshrrev_b32_e32 v187, 8, v186
	v_lshl_add_u32 v186, v187, 4, v186
	ds_read_b128 v[186:189], v186 offset:43216
	s_waitcnt vmcnt(0) lgkmcnt(0)
	v_mfma_f32_16x16x32_bf16 v[170:173], v[186:189], v[182:185], v[170:173]
	v_lshl_add_u64 v[186:187], v[192:193], 0, v[38:39]
	v_subrev_u32_e32 v186, s85, v186
	v_lshrrev_b32_e32 v187, 8, v186
	v_lshl_add_u32 v186, v187, 4, v186
	ds_read_b128 v[186:189], v186 offset:43216
	s_waitcnt vmcnt(0) lgkmcnt(0)
	v_mfma_f32_16x16x32_bf16 v[174:177], v[186:189], v[182:185], v[174:177]
	v_lshl_add_u64 v[186:187], v[192:193], 0, v[40:41]
	v_subrev_u32_e32 v186, s85, v186
	v_lshrrev_b32_e32 v187, 8, v186
	v_lshl_add_u32 v186, v187, 4, v186
	ds_read_b128 v[186:189], v186 offset:43216
	s_waitcnt vmcnt(0) lgkmcnt(0)
	v_mfma_f32_16x16x32_bf16 v[178:181], v[186:189], v[182:185], v[178:181]
	v_lshl_add_u64 v[186:187], v[192:193], 0, v[42:43]
	v_subrev_u32_e32 v186, s85, v186
	v_lshrrev_b32_e32 v187, 8, v186
	v_lshl_add_u32 v186, v187, 4, v186
	ds_read_b128 v[186:189], v186 offset:43216
	s_waitcnt vmcnt(0) lgkmcnt(0)
	v_mfma_f32_16x16x32_bf16 v[182:185], v[186:189], v[182:185], v[2:5]
	global_load_dwordx4 v[186:189], v[0:1], off offset:448
	s_nop 1
	v_subrev_u32_e32 v0, s85, v190
	v_lshrrev_b32_e32 v1, 8, v0
	v_lshl_add_u32 v0, v1, 4, v0
	ds_read_b128 v[0:3], v0 offset:43408
	s_waitcnt vmcnt(0) lgkmcnt(0)
; __device__ __forceinline__ f32x4 mfma16(bf16x8 a, bf16x8 b, f32x4 c) { return __builtin_amdgcn_mfma_f32_16x16x32_bf16(a, b, c, 0, 0, 0); }
; __device__ void ph_score(const P& p, int* lds) {
;     ...
;       for (int ks = 0; ks < 4; ++ks) {
;         bf16x8 qf = *(const bf16x8*)(Qb + tok * 2048 + h * 256 + half * 128 + ks * 32 + fq * 8);
; #pragma unroll
;         for (int mt = 0; mt < 8; ++mt) {
;           bf16x8 kf = *(const bf16x8*)(Kb + (mt * 16 + fr) * 128 + ks * 32 + fq * 8);
;           sc[mt] = mfma16(kf, qf, sc[mt]);
;         }
;       }
;       int a[16], b[16];
; #pragma unroll
;       for (int mt = 0; mt < 4; ++mt)
; #pragma unroll
;         for (int r = 0; r < 4; ++r) {
;           a[mt * 4 + r] = key_pack(sc[mt][r], mt * 16 + fq * 4 + r, 0x7f);
;           b[mt * 4 + r] = key_pack(sc[mt + 4][r], (mt + 4) * 16 + fq * 4 + r, 0x7f);
;         }
	v_mfma_f32_16x16x32_bf16 v[190:193], v[0:3], v[186:189], v[6:9]
	v_lshl_add_u64 v[0:1], v[194:195], 0, v[30:31]
	v_subrev_u32_e32 v0, s85, v0
	v_lshrrev_b32_e32 v1, 8, v0
	v_lshl_add_u32 v0, v1, 4, v0
	ds_read_b128 v[0:3], v0 offset:43216
	s_nop 0
	v_lshl_add_u64 v[8:9], v[194:195], 0, v[36:37]
	s_nop 3
	v_and_b32_e32 v48, 0xffffff80, v190
	s_waitcnt vmcnt(0) lgkmcnt(0)
	v_mfma_f32_16x16x32_bf16 v[12:15], v[0:3], v[186:189], v[10:13]
	v_lshl_add_u64 v[0:1], v[194:195], 0, v[32:33]
	v_subrev_u32_e32 v0, s85, v0
	v_lshrrev_b32_e32 v1, 8, v0
	v_lshl_add_u32 v0, v1, 4, v0
	ds_read_b128 v[0:3], v0 offset:43216
	s_nop 0
	v_subrev_u32_e32 v8, s85, v8
	v_lshrrev_b32_e32 v9, 8, v8
	v_lshl_add_u32 v8, v9, 4, v8
	ds_read_b128 v[8:11], v8 offset:43216
	s_waitcnt vmcnt(0) lgkmcnt(0)
	v_mfma_f32_16x16x32_bf16 v[4:7], v[0:3], v[186:189], v[162:165]
	v_lshl_add_u64 v[0:1], v[194:195], 0, v[34:35]
	v_subrev_u32_e32 v0, s85, v0
	v_lshrrev_b32_e32 v1, 8, v0
	v_lshl_add_u32 v0, v1, 4, v0
	ds_read_b128 v[0:3], v0 offset:43216
	s_waitcnt vmcnt(0) lgkmcnt(0)
	v_mfma_f32_16x16x32_bf16 v[162:165], v[8:11], v[186:189], v[170:173]
	v_lshl_add_u64 v[8:9], v[194:195], 0, v[38:39]
	v_subrev_u32_e32 v8, s85, v8
	v_lshrrev_b32_e32 v9, 8, v8
	v_lshl_add_u32 v8, v9, 4, v8
	ds_read_b128 v[8:11], v8 offset:43216
	s_waitcnt vmcnt(0) lgkmcnt(0)
	v_mfma_f32_16x16x32_bf16 v[0:3], v[0:3], v[186:189], v[166:169]
	v_lshl_add_u64 v[170:171], v[194:195], 0, v[42:43]
	v_subrev_u32_e32 v170, s85, v170
	v_lshrrev_b32_e32 v171, 8, v170
	v_lshl_add_u32 v170, v171, 4, v170
	ds_read_b128 v[170:173], v170 offset:43216
	s_waitcnt vmcnt(0) lgkmcnt(0)
	v_mfma_f32_16x16x32_bf16 v[166:169], v[8:11], v[186:189], v[174:177]
	v_lshl_add_u64 v[8:9], v[194:195], 0, v[40:41]
	v_subrev_u32_e32 v8, s85, v8
	v_lshrrev_b32_e32 v9, 8, v8
	v_lshl_add_u32 v8, v9, 4, v8
	ds_read_b128 v[8:11], v8 offset:43216
	s_nop 0
	v_ashrrev_i32_e32 v174, 31, v190
	v_and_b32_e32 v174, 0x7fffffff, v174
	v_bitop3_b32 v48, v48, v174, v20 bitop3:0x36
	v_and_b32_e32 v174, 0xffffff80, v162
	v_ashrrev_i32_e32 v162, 31, v162
	v_and_b32_e32 v162, 0x7fffffff, v162
	v_ashrrev_i32_e32 v175, 31, v191
	v_bitop3_b32 v162, v174, v162, v56 bitop3:0x36
	v_and_b32_e32 v174, 0xffffff80, v191
	v_and_b32_e32 v175, 0x7fffffff, v175
	v_bitop3_b32 v174, v174, v175, v57 bitop3:0x36
	v_and_b32_e32 v175, 0xffffff80, v163
	v_ashrrev_i32_e32 v163, 31, v163
	v_and_b32_e32 v163, 0x7fffffff, v163
	v_ashrrev_i32_e32 v176, 31, v192
	v_bitop3_b32 v163, v175, v163, v58 bitop3:0x36
	v_and_b32_e32 v175, 0xffffff80, v192
	v_and_b32_e32 v176, 0x7fffffff, v176
	v_bitop3_b32 v175, v175, v176, v59 bitop3:0x36
	v_and_b32_e32 v176, 0xffffff80, v164
	v_ashrrev_i32_e32 v164, 31, v164
	v_and_b32_e32 v164, 0x7fffffff, v164
	v_ashrrev_i32_e32 v177, 31, v193
	v_bitop3_b32 v164, v176, v164, v60 bitop3:0x36
	v_and_b32_e32 v176, 0xffffff80, v193
	v_and_b32_e32 v177, 0x7fffffff, v177
	v_bitop3_b32 v176, v176, v177, v61 bitop3:0x36
	v_and_b32_e32 v177, 0xffffff80, v165
	v_ashrrev_i32_e32 v165, 31, v165
	v_and_b32_e32 v165, 0x7fffffff, v165
	v_bitop3_b32 v165, v177, v165, v62 bitop3:0x36
	v_and_b32_e32 v177, 0xffffff80, v12
	v_ashrrev_i32_e32 v12, 31, v12
	v_and_b32_e32 v12, 0x7fffffff, v12
	v_bitop3_b32 v12, v177, v12, v63 bitop3:0x36
	v_and_b32_e32 v177, 0xffffff80, v166
	v_ashrrev_i32_e32 v166, 31, v166
	v_and_b32_e32 v166, 0x7fffffff, v166
	v_bitop3_b32 v166, v177, v166, v64 bitop3:0x36
	v_and_b32_e32 v177, 0xffffff80, v13
	v_ashrrev_i32_e32 v13, 31, v13
	v_and_b32_e32 v13, 0x7fffffff, v13
	v_bitop3_b32 v13, v177, v13, v65 bitop3:0x36
	v_and_b32_e32 v177, 0xffffff80, v167
	v_ashrrev_i32_e32 v167, 31, v167
	v_and_b32_e32 v167, 0x7fffffff, v167
	v_bitop3_b32 v167, v177, v167, v66 bitop3:0x36
	v_and_b32_e32 v177, 0xffffff80, v14
	v_ashrrev_i32_e32 v14, 31, v14
	v_and_b32_e32 v14, 0x7fffffff, v14
	v_bitop3_b32 v14, v177, v14, v67 bitop3:0x36
	v_and_b32_e32 v177, 0xffffff80, v168
	v_ashrrev_i32_e32 v168, 31, v168
	v_and_b32_e32 v168, 0x7fffffff, v168
	v_bitop3_b32 v168, v177, v168, v68 bitop3:0x36
	v_and_b32_e32 v177, 0xffffff80, v15
	v_ashrrev_i32_e32 v15, 31, v15
	v_and_b32_e32 v15, 0x7fffffff, v15
	s_waitcnt vmcnt(0) lgkmcnt(0)
	v_mfma_f32_16x16x32_bf16 v[8:11], v[8:11], v[186:189], v[178:181]
	v_bitop3_b32 v15, v177, v15, v69 bitop3:0x36
	v_and_b32_e32 v177, 0xffffff80, v169
	v_ashrrev_i32_e32 v169, 31, v169
	v_and_b32_e32 v169, 0x7fffffff, v169
	v_bitop3_b32 v169, v177, v169, v70 bitop3:0x36
	v_and_b32_e32 v177, 0xffffff80, v4
	v_ashrrev_i32_e32 v4, 31, v4
	v_and_b32_e32 v4, 0x7fffffff, v4
	v_bitop3_b32 v4, v177, v4, v71 bitop3:0x36
	v_and_b32_e32 v177, 0xffffff80, v8
	v_ashrrev_i32_e32 v8, 31, v8
	v_and_b32_e32 v8, 0x7fffffff, v8
	v_bitop3_b32 v8, v177, v8, v72 bitop3:0x36
	v_and_b32_e32 v177, 0xffffff80, v5
	v_ashrrev_i32_e32 v5, 31, v5
	v_and_b32_e32 v5, 0x7fffffff, v5
	v_bitop3_b32 v5, v177, v5, v73 bitop3:0x36
	v_and_b32_e32 v177, 0xffffff80, v9
	v_ashrrev_i32_e32 v9, 31, v9
	v_and_b32_e32 v9, 0x7fffffff, v9
	v_bitop3_b32 v9, v177, v9, v74 bitop3:0x36
	v_and_b32_e32 v177, 0xffffff80, v6
	v_ashrrev_i32_e32 v6, 31, v6
	v_and_b32_e32 v6, 0x7fffffff, v6
	v_bitop3_b32 v6, v177, v6, v75 bitop3:0x36
	v_and_b32_e32 v177, 0xffffff80, v10
	v_ashrrev_i32_e32 v10, 31, v10
	v_and_b32_e32 v10, 0x7fffffff, v10
	v_bitop3_b32 v10, v177, v10, v76 bitop3:0x36
	v_and_b32_e32 v177, 0xffffff80, v7
	v_ashrrev_i32_e32 v7, 31, v7
	v_and_b32_e32 v7, 0x7fffffff, v7
	v_mfma_f32_16x16x32_bf16 v[170:173], v[170:173], v[186:189], v[182:185]
	v_bitop3_b32 v7, v177, v7, v77 bitop3:0x36
	v_and_b32_e32 v177, 0xffffff80, v11
	v_ashrrev_i32_e32 v11, 31, v11
	v_and_b32_e32 v11, 0x7fffffff, v11
; __device__ __forceinline__ void sort16p(int (&v)[16]) {
; #pragma unroll
;   for (int k = 2; k <= 16; k <<= 1)
; #pragma unroll
;     for (int j = k >> 1; j > 0; j >>= 1)
; #pragma unroll
;       for (int i = 0; i < 16; ++i) {
;         int l = i ^ j;
;         if (l > i) {
;           if ((i & k) == 0) { CE1(v[i], v[l]); }
;           else { CE1(v[l], v[i]); }
;         }
;       }
; }
; __device__ void ph_score(const P& p, int* lds) {
;     ...
; #pragma unroll
;       for (int mt = 0; mt < 4; ++mt)
; #pragma unroll
;         for (int r = 0; r < 4; ++r) {
;           a[mt * 4 + r] = key_pack(sc[mt][r], mt * 16 + fq * 4 + r, 0x7f);
;           b[mt * 4 + r] = key_pack(sc[mt + 4][r], (mt + 4) * 16 + fq * 4 + r, 0x7f);
;         }
;       sort16p(a);
	v_bitop3_b32 v11, v177, v11, v78 bitop3:0x36
	v_and_b32_e32 v177, 0xffffff80, v0
	v_ashrrev_i32_e32 v0, 31, v0
	v_and_b32_e32 v0, 0x7fffffff, v0
	v_bitop3_b32 v0, v177, v0, v79 bitop3:0x36
	v_and_b32_e32 v177, 0xffffff80, v170
	v_ashrrev_i32_e32 v170, 31, v170
	v_and_b32_e32 v170, 0x7fffffff, v170
	v_bitop3_b32 v170, v177, v170, v80 bitop3:0x36
	v_and_b32_e32 v177, 0xffffff80, v1
	v_ashrrev_i32_e32 v1, 31, v1
	v_and_b32_e32 v1, 0x7fffffff, v1
	v_bitop3_b32 v1, v177, v1, v81 bitop3:0x36
	v_and_b32_e32 v177, 0xffffff80, v171
	v_ashrrev_i32_e32 v171, 31, v171
	v_and_b32_e32 v171, 0x7fffffff, v171
	v_bitop3_b32 v171, v177, v171, v82 bitop3:0x36
	v_and_b32_e32 v177, 0xffffff80, v2
	v_ashrrev_i32_e32 v2, 31, v2
	v_and_b32_e32 v2, 0x7fffffff, v2
	v_bitop3_b32 v2, v177, v2, v83 bitop3:0x36
	v_and_b32_e32 v177, 0xffffff80, v172
	v_ashrrev_i32_e32 v172, 31, v172
	v_and_b32_e32 v172, 0x7fffffff, v172
	v_bitop3_b32 v172, v177, v172, v84 bitop3:0x36
	v_and_b32_e32 v177, 0xffffff80, v3
	v_ashrrev_i32_e32 v3, 31, v3
	v_and_b32_e32 v3, 0x7fffffff, v3
	v_bitop3_b32 v3, v177, v3, v85 bitop3:0x36
	v_and_b32_e32 v177, 0xffffff80, v173
	v_ashrrev_i32_e32 v173, 31, v173
	v_and_b32_e32 v173, 0x7fffffff, v173
	v_bitop3_b32 v173, v177, v173, v86 bitop3:0x36
	v_max_i32_e32 v177, v48, v174
	v_min_i32_e32 v48, v48, v174
	v_max_i32_e32 v174, v176, v175
	v_min_i32_e32 v175, v176, v175
	v_max_i32_e32 v176, v12, v13
	v_min_i32_e32 v12, v12, v13
	v_max_i32_e32 v13, v15, v14
	v_min_i32_e32 v14, v15, v14
	v_max_i32_e32 v15, v4, v5
	v_min_i32_e32 v4, v4, v5
	v_max_i32_e32 v5, v7, v6
	v_min_i32_e32 v6, v7, v6
	v_max_i32_e32 v7, v0, v1
	v_min_i32_e32 v0, v0, v1
	v_max_i32_e32 v1, v3, v2
	v_min_i32_e32 v2, v3, v2
	v_max_i32_e32 v3, v177, v175
	v_min_i32_e32 v175, v177, v175
	v_max_i32_e32 v177, v48, v174
	v_min_i32_e32 v48, v48, v174
	v_max_i32_e32 v174, v14, v176
	v_min_i32_e32 v14, v14, v176
	v_max_i32_e32 v176, v13, v12
	v_min_i32_e32 v12, v13, v12
	v_max_i32_e32 v13, v15, v6
	v_min_i32_e32 v6, v15, v6
	v_max_i32_e32 v15, v4, v5
	v_min_i32_e32 v4, v4, v5
	v_max_i32_e32 v5, v2, v7
	v_min_i32_e32 v2, v2, v7
	v_max_i32_e32 v7, v1, v0
	v_min_i32_e32 v0, v1, v0
	v_max_i32_e32 v1, v3, v177
	v_min_i32_e32 v3, v3, v177
	v_max_i32_e32 v177, v175, v48
	v_min_i32_e32 v48, v175, v48
	v_max_i32_e32 v175, v12, v14
	v_min_i32_e32 v12, v12, v14
	v_max_i32_e32 v14, v176, v174
	v_min_i32_e32 v174, v176, v174
	v_max_i32_e32 v176, v13, v15
	v_min_i32_e32 v13, v13, v15
	v_max_i32_e32 v15, v6, v4
	v_min_i32_e32 v4, v6, v4
	v_max_i32_e32 v6, v0, v2
	v_min_i32_e32 v0, v0, v2
	v_max_i32_e32 v2, v7, v5
	v_min_i32_e32 v5, v7, v5
	v_max_i32_e32 v7, v1, v12
	v_min_i32_e32 v1, v1, v12
	v_max_i32_e32 v12, v3, v175
	v_min_i32_e32 v3, v3, v175
	v_max_i32_e32 v175, v177, v174
	v_min_i32_e32 v174, v177, v174
	v_max_i32_e32 v177, v48, v14
	v_min_i32_e32 v14, v48, v14
	v_max_i32_e32 v48, v0, v176
	v_min_i32_e32 v0, v0, v176
	v_max_i32_e32 v176, v6, v13
	v_min_i32_e32 v6, v6, v13
	v_max_i32_e32 v13, v5, v15
	v_min_i32_e32 v5, v5, v15
	v_max_i32_e32 v15, v2, v4
	v_min_i32_e32 v2, v2, v4
	v_max_i32_e32 v4, v7, v175
	v_min_i32_e32 v7, v7, v175
	v_max_i32_e32 v175, v12, v177
	v_min_i32_e32 v12, v12, v177
	v_max_i32_e32 v177, v1, v174
	v_min_i32_e32 v1, v1, v174
	v_max_i32_e32 v174, v3, v14
	v_min_i32_e32 v3, v3, v14
	v_max_i32_e32 v14, v5, v0
	v_min_i32_e32 v0, v5, v0
	v_max_i32_e32 v5, v2, v6
	v_min_i32_e32 v2, v2, v6
	v_max_i32_e32 v6, v13, v48
	v_min_i32_e32 v13, v13, v48
	v_max_i32_e32 v48, v15, v176
	v_min_i32_e32 v15, v15, v176
	v_max_i32_e32 v176, v4, v175
	v_min_i32_e32 v4, v4, v175
	v_max_i32_e32 v175, v7, v12
	v_min_i32_e32 v7, v7, v12
	v_max_i32_e32 v12, v177, v174
	v_min_i32_e32 v174, v177, v174
	v_max_i32_e32 v177, v1, v3
	v_min_i32_e32 v1, v1, v3
	v_max_i32_e32 v3, v2, v0
	v_min_i32_e32 v0, v2, v0
	v_max_i32_e32 v2, v5, v14
	v_min_i32_e32 v5, v5, v14
	v_max_i32_e32 v14, v15, v13
	v_min_i32_e32 v13, v15, v13
	v_max_i32_e32 v15, v48, v6
	v_min_i32_e32 v6, v48, v6
	v_max_i32_e32 v48, v176, v0
	v_min_i32_e32 v0, v176, v0
	v_max_i32_e32 v176, v4, v3
	v_min_i32_e32 v3, v4, v3
	v_max_i32_e32 v4, v175, v5
	v_min_i32_e32 v5, v175, v5
	v_max_i32_e32 v175, v7, v2
	v_min_i32_e32 v2, v7, v2
	v_max_i32_e32 v7, v12, v13
	v_min_i32_e32 v12, v12, v13
	v_max_i32_e32 v13, v174, v14
	v_min_i32_e32 v14, v174, v14
	v_max_i32_e32 v174, v177, v6
	v_min_i32_e32 v6, v177, v6
	v_max_i32_e32 v177, v1, v15
	v_min_i32_e32 v1, v1, v15
	v_max_i32_e32 v15, v48, v7
	v_min_i32_e32 v7, v48, v7
	v_max_i32_e32 v48, v176, v13
	v_min_i32_e32 v13, v176, v13
	v_max_i32_e32 v176, v4, v174
	v_min_i32_e32 v4, v4, v174
	v_max_i32_e32 v174, v175, v177
	v_min_i32_e32 v175, v175, v177
	v_max_i32_e32 v177, v0, v12
	v_min_i32_e32 v0, v0, v12
	v_max_i32_e32 v12, v3, v14
	v_min_i32_e32 v3, v3, v14
	v_max_i32_e32 v14, v5, v6
	v_min_i32_e32 v5, v5, v6
	v_max_i32_e32 v6, v2, v1
	v_min_i32_e32 v1, v2, v1
	v_max_i32_e32 v2, v15, v176
	v_min_i32_e32 v15, v15, v176
	v_max_i32_e32 v176, v48, v174
	v_min_i32_e32 v48, v48, v174
	v_max_i32_e32 v174, v7, v4
	v_min_i32_e32 v4, v7, v4
	v_max_i32_e32 v7, v13, v175
	v_min_i32_e32 v13, v13, v175
	v_max_i32_e32 v175, v177, v14
	v_min_i32_e32 v14, v177, v14
	v_max_i32_e32 v177, v12, v6
	v_min_i32_e32 v6, v12, v6
	v_max_i32_e32 v12, v0, v5
	v_min_i32_e32 v0, v0, v5
	v_max_i32_e32 v5, v3, v1
	v_min_i32_e32 v1, v3, v1
	v_min_i32_e32 v3, v2, v176
	v_min_i32_e32 v178, v15, v48
	v_min_i32_e32 v179, v174, v7
	v_min_i32_e32 v180, v4, v13
	v_min_i32_e32 v181, v175, v177
	v_min_i32_e32 v182, v14, v6
	v_min_i32_e32 v183, v12, v5
	v_min_i32_e32 v184, v0, v1
	v_max_i32_e32 v185, v162, v163
	v_min_i32_e32 v162, v162, v163
; __device__ __forceinline__ void sort16p(int (&v)[16]) {
; #pragma unroll
;   for (int k = 2; k <= 16; k <<= 1)
; #pragma unroll
;     for (int j = k >> 1; j > 0; j >>= 1)
; #pragma unroll
;       for (int i = 0; i < 16; ++i) {
;         int l = i ^ j;
;         if (l > i) {
;           if ((i & k) == 0) { CE1(v[i], v[l]); }
;           else { CE1(v[l], v[i]); }
;         }
;       }
; }
; __device__ __forceinline__ void merge16p(int (&a)[16], const int (&b)[16]) {
; #pragma unroll
;   for (int i = 0; i < 16; ++i) a[i] = max(a[i], b[15 - i]);
; #pragma unroll
;   for (int j = 8; j > 0; j >>= 1)
; #pragma unroll
;     for (int i = 0; i < 16; ++i) {
;       int l = i ^ j;
;       if (l > i) { CE1(a[i], a[l]); }
;     }
; }
; __device__ void ph_score(const P& p, int* lds) {
;     ...
;       sort16p(b);
;       __builtin_amdgcn_sched_barrier(0);
;       merge16p(a, b);
	v_max_i32_e32 v163, v165, v164
	v_min_i32_e32 v164, v165, v164
	v_max_i32_e32 v165, v166, v167
	v_min_i32_e32 v166, v166, v167
	v_max_i32_e32 v167, v169, v168
	v_min_i32_e32 v168, v169, v168
	v_max_i32_e32 v169, v8, v9
	v_min_i32_e32 v8, v8, v9
	v_max_i32_e32 v9, v11, v10
	v_min_i32_e32 v10, v11, v10
	v_max_i32_e32 v11, v170, v171
	v_min_i32_e32 v170, v170, v171
	v_max_i32_e32 v171, v173, v172
	v_min_i32_e32 v172, v173, v172
	v_max_i32_e32 v173, v185, v164
	v_min_i32_e32 v164, v185, v164
	v_max_i32_e32 v185, v162, v163
	v_min_i32_e32 v162, v162, v163
	v_max_i32_e32 v163, v168, v165
	v_min_i32_e32 v165, v168, v165
	v_max_i32_e32 v168, v167, v166
	v_min_i32_e32 v166, v167, v166
	v_max_i32_e32 v167, v169, v10
	v_min_i32_e32 v10, v169, v10
	v_max_i32_e32 v169, v8, v9
	v_min_i32_e32 v8, v8, v9
	v_max_i32_e32 v9, v172, v11
	v_min_i32_e32 v11, v172, v11
	v_max_i32_e32 v172, v171, v170
	v_min_i32_e32 v170, v171, v170
	v_max_i32_e32 v171, v173, v185
	v_min_i32_e32 v173, v173, v185
	v_max_i32_e32 v185, v164, v162
	v_min_i32_e32 v162, v164, v162
	v_max_i32_e32 v164, v166, v165
	v_min_i32_e32 v165, v166, v165
	v_max_i32_e32 v166, v168, v163
	v_min_i32_e32 v163, v168, v163
	v_max_i32_e32 v168, v167, v169
	v_min_i32_e32 v167, v167, v169
	v_max_i32_e32 v169, v10, v8
	v_min_i32_e32 v8, v10, v8
	v_max_i32_e32 v10, v170, v11
	v_min_i32_e32 v11, v170, v11
	v_max_i32_e32 v170, v172, v9
	v_min_i32_e32 v9, v172, v9
	v_max_i32_e32 v172, v171, v165
	v_min_i32_e32 v165, v171, v165
	v_max_i32_e32 v171, v173, v164
	v_min_i32_e32 v164, v173, v164
	v_max_i32_e32 v173, v185, v163
	v_min_i32_e32 v163, v185, v163
	v_max_i32_e32 v185, v162, v166
	v_min_i32_e32 v162, v162, v166
	v_max_i32_e32 v166, v11, v168
	v_min_i32_e32 v11, v11, v168
	v_max_i32_e32 v168, v10, v167
	v_min_i32_e32 v10, v10, v167
	v_max_i32_e32 v167, v9, v169
	v_min_i32_e32 v9, v9, v169
	v_max_i32_e32 v169, v170, v8
	v_min_i32_e32 v8, v170, v8
	v_max_i32_e32 v170, v172, v173
	v_min_i32_e32 v172, v172, v173
	v_max_i32_e32 v173, v171, v185
	v_min_i32_e32 v171, v171, v185
	v_max_i32_e32 v185, v165, v163
	v_min_i32_e32 v163, v165, v163
	v_max_i32_e32 v165, v164, v162
	v_min_i32_e32 v162, v164, v162
	v_max_i32_e32 v164, v9, v11
	v_min_i32_e32 v9, v9, v11
	v_max_i32_e32 v11, v8, v10
	v_min_i32_e32 v8, v8, v10
	v_max_i32_e32 v10, v167, v166
	v_min_i32_e32 v166, v167, v166
	v_max_i32_e32 v167, v169, v168
	v_min_i32_e32 v168, v169, v168
	v_max_i32_e32 v169, v170, v173
	v_min_i32_e32 v170, v170, v173
	v_max_i32_e32 v173, v172, v171
	v_min_i32_e32 v171, v172, v171
	v_max_i32_e32 v172, v185, v165
	v_min_i32_e32 v165, v185, v165
	v_max_i32_e32 v185, v163, v162
	v_min_i32_e32 v162, v163, v162
	v_max_i32_e32 v163, v8, v9
	v_min_i32_e32 v8, v8, v9
	v_max_i32_e32 v9, v11, v164
	v_min_i32_e32 v11, v11, v164
	v_max_i32_e32 v164, v168, v166
	v_min_i32_e32 v166, v168, v166
	v_max_i32_e32 v168, v167, v10
	v_min_i32_e32 v10, v167, v10
	v_max_i32_e32 v167, v169, v8
	v_min_i32_e32 v8, v169, v8
	v_max_i32_e32 v169, v170, v163
	v_min_i32_e32 v163, v170, v163
	v_max_i32_e32 v170, v173, v11
	v_min_i32_e32 v11, v173, v11
	v_max_i32_e32 v173, v171, v9
	v_min_i32_e32 v9, v171, v9
	v_max_i32_e32 v171, v172, v166
	v_min_i32_e32 v166, v172, v166
	v_max_i32_e32 v172, v165, v164
	v_min_i32_e32 v164, v165, v164
	v_max_i32_e32 v165, v185, v10
	v_min_i32_e32 v10, v185, v10
	v_max_i32_e32 v185, v162, v168
	v_min_i32_e32 v162, v162, v168
	v_max_i32_e32 v168, v167, v171
	v_min_i32_e32 v167, v167, v171
	v_max_i32_e32 v171, v169, v172
	v_min_i32_e32 v169, v169, v172
	v_max_i32_e32 v172, v170, v165
	v_min_i32_e32 v165, v170, v165
	v_max_i32_e32 v170, v173, v185
	v_min_i32_e32 v173, v173, v185
	v_max_i32_e32 v185, v8, v166
	v_min_i32_e32 v8, v8, v166
	v_max_i32_e32 v166, v163, v164
	v_min_i32_e32 v163, v163, v164
	v_max_i32_e32 v164, v11, v10
	v_min_i32_e32 v10, v11, v10
	v_max_i32_e32 v11, v9, v162
	v_min_i32_e32 v9, v9, v162
	v_max_i32_e32 v162, v168, v172
	v_min_i32_e32 v168, v168, v172
	v_max_i32_e32 v172, v171, v170
	v_min_i32_e32 v170, v171, v170
	v_max_i32_e32 v171, v167, v165
	v_min_i32_e32 v165, v167, v165
	v_max_i32_e32 v167, v169, v173
	v_min_i32_e32 v169, v169, v173
	v_max_i32_e32 v173, v185, v164
	v_min_i32_e32 v164, v185, v164
	v_max_i32_e32 v185, v166, v11
	v_min_i32_e32 v11, v166, v11
	v_max_i32_e32 v166, v8, v10
	v_min_i32_e32 v8, v8, v10
	v_max_i32_e32 v10, v163, v9
	v_min_i32_e32 v9, v163, v9
	v_min_i32_e32 v163, v162, v172
	v_min_i32_e32 v186, v168, v170
	v_min_i32_e32 v187, v171, v167
	v_min_i32_e32 v188, v165, v169
	v_min_i32_e32 v189, v173, v185
	v_min_i32_e32 v190, v164, v11
	v_min_i32_e32 v191, v166, v10
	v_min_i32_e32 v192, v8, v9
	v_max3_i32 v2, v2, v176, v192
	v_max3_i32 v3, v3, v8, v9
	v_max3_i32 v8, v15, v48, v191
	v_max3_i32 v9, v178, v166, v10
	v_max3_i32 v7, v174, v7, v190
	v_max3_i32 v10, v179, v164, v11
	v_max3_i32 v4, v4, v13, v189
	v_max3_i32 v11, v180, v173, v185
	v_max3_i32 v13, v175, v177, v188
	v_max3_i32 v15, v181, v165, v169
	v_max3_i32 v6, v14, v6, v187
	v_max3_i32 v14, v182, v171, v167
	v_max3_i32 v5, v12, v5, v186
	v_max3_i32 v12, v183, v168, v170
	v_max3_i32 v0, v0, v1, v163
	v_max3_i32 v1, v184, v162, v172
	v_max_i32_e32 v48, v2, v13
	v_min_i32_e32 v2, v2, v13
	v_max_i32_e32 v13, v3, v15
	v_min_i32_e32 v3, v3, v15
	v_max_i32_e32 v15, v8, v6
	v_min_i32_e32 v6, v8, v6
	v_max_i32_e32 v8, v9, v14
	v_min_i32_e32 v9, v9, v14
	v_max_i32_e32 v14, v7, v5
	v_min_i32_e32 v5, v7, v5
	v_max_i32_e32 v7, v10, v12
	v_min_i32_e32 v10, v10, v12
	v_max_i32_e32 v12, v4, v0
	v_min_i32_e32 v0, v4, v0
	v_max_i32_e32 v4, v11, v1
	v_min_i32_e32 v1, v11, v1
	v_max_i32_e32 v11, v48, v14
	v_min_i32_e32 v14, v48, v14
; __device__ __forceinline__ void merge16p(int (&a)[16], const int (&b)[16]) {
; #pragma unroll
;   for (int i = 0; i < 16; ++i) a[i] = max(a[i], b[15 - i]);
; #pragma unroll
;   for (int j = 8; j > 0; j >>= 1)
; #pragma unroll
;     for (int i = 0; i < 16; ++i) {
;       int l = i ^ j;
;       if (l > i) { CE1(a[i], a[l]); }
;     }
; }
; __device__ __forceinline__ void xmerge16p(int (&a)[16], int mask) {
;   int b[16];
; #pragma unroll
;   for (int i = 0; i < 16; ++i) b[i] = (mask == 16) ? __builtin_amdgcn_ds_swizzle(a[i], 0x401F) : __shfl_xor(a[i], 32);
;   merge16p(a, b);
; }
; __device__ void ph_score(const P& p, int* lds) {
;     ...
;       xmerge16p(a, 16); xmerge16p(a, 32);
	v_max_i32_e32 v48, v13, v7
	v_min_i32_e32 v7, v13, v7
	v_max_i32_e32 v13, v15, v12
	v_min_i32_e32 v12, v15, v12
	v_max_i32_e32 v15, v8, v4
	v_min_i32_e32 v4, v8, v4
	v_max_i32_e32 v8, v2, v5
	v_min_i32_e32 v2, v2, v5
	v_max_i32_e32 v5, v3, v10
	v_min_i32_e32 v3, v3, v10
	v_max_i32_e32 v10, v6, v0
	v_min_i32_e32 v0, v6, v0
	v_max_i32_e32 v6, v9, v1
	v_min_i32_e32 v1, v9, v1
	v_max_i32_e32 v9, v11, v13
	v_min_i32_e32 v11, v11, v13
	v_max_i32_e32 v13, v48, v15
	v_min_i32_e32 v15, v48, v15
	v_max_i32_e32 v48, v14, v12
	v_min_i32_e32 v12, v14, v12
	v_max_i32_e32 v14, v7, v4
	v_min_i32_e32 v4, v7, v4
	v_max_i32_e32 v7, v8, v10
	v_min_i32_e32 v8, v8, v10
	v_max_i32_e32 v10, v5, v6
	v_min_i32_e32 v5, v5, v6
	v_max_i32_e32 v6, v2, v0
	v_min_i32_e32 v0, v2, v0
	v_max_i32_e32 v2, v3, v1
	v_min_i32_e32 v1, v3, v1
	v_max_i32_e32 v3, v9, v13
	v_min_i32_e32 v9, v9, v13
	v_max_i32_e32 v13, v11, v15
	v_min_i32_e32 v11, v11, v15
	v_max_i32_e32 v15, v48, v14
	v_min_i32_e32 v14, v48, v14
	v_max_i32_e32 v48, v12, v4
	v_min_i32_e32 v4, v12, v4
	v_max_i32_e32 v12, v7, v10
	v_min_i32_e32 v7, v7, v10
	v_max_i32_e32 v10, v8, v5
	v_min_i32_e32 v5, v8, v5
	v_max_i32_e32 v8, v6, v2
	v_min_i32_e32 v2, v6, v2
	v_max_i32_e32 v6, v0, v1
	v_min_i32_e32 v0, v0, v1
	ds_swizzle_b32 v1, v3 offset:swizzle(SWAP,16)
	ds_swizzle_b32 v162, v9 offset:swizzle(SWAP,16)
	ds_swizzle_b32 v163, v13 offset:swizzle(SWAP,16)
	ds_swizzle_b32 v164, v11 offset:swizzle(SWAP,16)
	ds_swizzle_b32 v165, v15 offset:swizzle(SWAP,16)
	ds_swizzle_b32 v166, v14 offset:swizzle(SWAP,16)
	ds_swizzle_b32 v167, v48 offset:swizzle(SWAP,16)
	ds_swizzle_b32 v168, v4 offset:swizzle(SWAP,16)
	ds_swizzle_b32 v169, v12 offset:swizzle(SWAP,16)
	ds_swizzle_b32 v170, v7 offset:swizzle(SWAP,16)
	ds_swizzle_b32 v171, v10 offset:swizzle(SWAP,16)
	ds_swizzle_b32 v172, v0 offset:swizzle(SWAP,16)
	ds_swizzle_b32 v173, v6 offset:swizzle(SWAP,16)
	ds_swizzle_b32 v174, v2 offset:swizzle(SWAP,16)
	ds_swizzle_b32 v175, v8 offset:swizzle(SWAP,16)
	ds_swizzle_b32 v176, v5 offset:swizzle(SWAP,16)
	s_waitcnt lgkmcnt(4)
	v_max_i32_e32 v3, v3, v172
	s_waitcnt lgkmcnt(3)
	v_max_i32_e32 v9, v9, v173
	s_waitcnt lgkmcnt(2)
	v_max_i32_e32 v13, v13, v174
	s_waitcnt lgkmcnt(1)
	v_max_i32_e32 v11, v11, v175
	s_waitcnt lgkmcnt(0)
	v_max_i32_e32 v15, v15, v176
	v_max_i32_e32 v14, v14, v171
	v_max_i32_e32 v48, v48, v170
	v_max_i32_e32 v4, v4, v169
	v_max_i32_e32 v12, v12, v168
	v_max_i32_e32 v7, v7, v167
	v_max_i32_e32 v10, v10, v166
	v_max_i32_e32 v5, v5, v165
	v_max_i32_e32 v8, v8, v164
	v_max_i32_e32 v2, v2, v163
	v_max_i32_e32 v6, v6, v162
	v_max_i32_e32 v0, v0, v1
	v_max_i32_e32 v1, v3, v12
	v_min_i32_e32 v3, v3, v12
	v_max_i32_e32 v12, v9, v7
	v_min_i32_e32 v7, v9, v7
	v_max_i32_e32 v9, v13, v10
	v_min_i32_e32 v10, v13, v10
	v_max_i32_e32 v13, v11, v5
	v_min_i32_e32 v5, v11, v5
	v_max_i32_e32 v11, v15, v8
	v_min_i32_e32 v8, v15, v8
	v_max_i32_e32 v15, v14, v2
	v_min_i32_e32 v2, v14, v2
	v_max_i32_e32 v14, v48, v6
	v_min_i32_e32 v6, v48, v6
	v_max_i32_e32 v48, v4, v0
	v_min_i32_e32 v0, v4, v0
	v_max_i32_e32 v4, v1, v11
	v_min_i32_e32 v1, v1, v11
	v_max_i32_e32 v11, v12, v15
	v_min_i32_e32 v12, v12, v15
	v_max_i32_e32 v15, v9, v14
	v_min_i32_e32 v9, v9, v14
	v_max_i32_e32 v14, v13, v48
	v_min_i32_e32 v13, v13, v48
	v_max_i32_e32 v48, v3, v8
	v_min_i32_e32 v3, v3, v8
	v_max_i32_e32 v8, v7, v2
	v_min_i32_e32 v2, v7, v2
	v_max_i32_e32 v7, v10, v6
	v_min_i32_e32 v6, v10, v6
	v_max_i32_e32 v10, v5, v0
	v_min_i32_e32 v0, v5, v0
	v_max_i32_e32 v5, v4, v15
	v_min_i32_e32 v4, v4, v15
	v_max_i32_e32 v15, v11, v14
	v_min_i32_e32 v11, v11, v14
	v_max_i32_e32 v14, v1, v9
	v_min_i32_e32 v1, v1, v9
	v_max_i32_e32 v9, v12, v13
	v_min_i32_e32 v12, v12, v13
	v_max_i32_e32 v13, v48, v7
	v_min_i32_e32 v7, v48, v7
	v_max_i32_e32 v48, v8, v10
	v_min_i32_e32 v8, v8, v10
	v_max_i32_e32 v10, v3, v6
	v_min_i32_e32 v3, v3, v6
	v_max_i32_e32 v6, v2, v0
	v_min_i32_e32 v0, v2, v0
	v_max_i32_e32 v2, v5, v15
	v_min_i32_e32 v5, v5, v15
	v_max_i32_e32 v15, v4, v11
	v_min_i32_e32 v4, v4, v11
	v_max_i32_e32 v11, v14, v9
	v_min_i32_e32 v9, v14, v9
	v_max_i32_e32 v14, v1, v12
	v_min_i32_e32 v1, v1, v12
	v_max_i32_e32 v12, v13, v48
	v_min_i32_e32 v13, v13, v48
	v_max_i32_e32 v48, v7, v8
	v_min_i32_e32 v7, v7, v8
	v_max_i32_e32 v8, v10, v6
	v_min_i32_e32 v6, v10, v6
	v_max_i32_e32 v10, v3, v0
	v_min_i32_e32 v0, v3, v0
	ds_bpermute_b32 v3, v54, v2
	ds_bpermute_b32 v162, v54, v5
	ds_bpermute_b32 v163, v54, v15
	ds_bpermute_b32 v164, v54, v4
	ds_bpermute_b32 v165, v54, v11
	ds_bpermute_b32 v166, v54, v9
	ds_bpermute_b32 v167, v54, v14
	ds_bpermute_b32 v168, v54, v1
	ds_bpermute_b32 v169, v54, v12
	ds_bpermute_b32 v170, v54, v13
	ds_bpermute_b32 v171, v54, v48
	ds_bpermute_b32 v172, v54, v0
	ds_bpermute_b32 v173, v54, v10
	ds_bpermute_b32 v174, v54, v6
	ds_bpermute_b32 v175, v54, v8
	ds_bpermute_b32 v176, v54, v7
	s_waitcnt lgkmcnt(4)
	v_max_i32_e32 v2, v2, v172
	s_waitcnt lgkmcnt(3)
	v_max_i32_e32 v5, v5, v173
	s_waitcnt lgkmcnt(2)
	v_max_i32_e32 v15, v15, v174
	s_waitcnt lgkmcnt(1)
	v_max_i32_e32 v4, v4, v175
	s_waitcnt lgkmcnt(0)
; __device__ void ph_score(const P& p, int* lds) {
;     ...
;       xmerge16p(a, 16); xmerge16p(a, 32);
;       __builtin_amdgcn_sched_barrier(0);
;       int idx4[4];
; #pragma unroll
;       for (int i = 0; i < 16; ++i) {
;         const int k = key_unmap(a[i]);
;         tv[half][i] = __int_as_float(k & ~0x7f);
;         if ((i >> 2) == 0) idx4[i & 3] = k & 0x7f;
;       }
; #pragma unroll
;       for (int i = 4; i < 16; ++i) {
;         const int k = key_unmap(a[i]) & 0x7f;
;         if ((i >> 2) == 1) idx4[i & 3] = (fq == 1) ? k : idx4[i & 3];
;         if ((i >> 2) == 2) idx4[i & 3] = (fq == 2) ? k : idx4[i & 3];
;         if ((i >> 2) == 3) idx4[i & 3] = (fq == 3) ? k : idx4[i & 3];
;       }
;       *(int4*)(myl + half * 16 + fq * 4) = make_int4(idx4[0], idx4[1], idx4[2], idx4[3]);
;     }
;     int L0[16];
; #pragma unroll
;     for (int rr = 0; rr < 4; ++rr) {
;       const float v1 = fq == 0 ? tv[0][rr] : (fq == 1 ? tv[0][4 + rr] : (fq == 2 ? tv[0][8 + rr] : tv[0][12 + rr]));
;       int Lr[16];
; #pragma unroll
;       for (int j = 0; j < 16; ++j) Lr[j] = key_pack(v1 + tv[1][j], ((fq * 4 + rr) << 4) | j, 0xff);
	v_max_i32_e32 v11, v11, v176
	v_max_i32_e32 v9, v9, v171
	v_max_i32_e32 v14, v14, v170
	v_max_i32_e32 v1, v1, v169
	v_max_i32_e32 v12, v12, v168
	v_max_i32_e32 v13, v13, v167
	v_max_i32_e32 v48, v48, v166
	v_max_i32_e32 v7, v7, v165
	v_max_i32_e32 v8, v8, v164
	v_max_i32_e32 v6, v6, v163
	v_max_i32_e32 v10, v10, v162
	v_max_i32_e32 v0, v0, v3
	v_max_i32_e32 v3, v2, v12
	v_min_i32_e32 v2, v2, v12
	v_max_i32_e32 v12, v5, v13
	v_min_i32_e32 v5, v5, v13
	v_max_i32_e32 v13, v15, v48
	v_min_i32_e32 v15, v15, v48
	v_max_i32_e32 v48, v4, v7
	v_min_i32_e32 v4, v4, v7
	v_max_i32_e32 v7, v11, v8
	v_min_i32_e32 v8, v11, v8
	v_max_i32_e32 v11, v9, v6
	v_min_i32_e32 v6, v9, v6
	v_max_i32_e32 v9, v14, v10
	v_min_i32_e32 v10, v14, v10
	v_max_i32_e32 v14, v1, v0
	v_min_i32_e32 v0, v1, v0
	v_max_i32_e32 v1, v3, v7
	v_min_i32_e32 v3, v3, v7
	v_max_i32_e32 v7, v12, v11
	v_min_i32_e32 v11, v12, v11
	v_max_i32_e32 v12, v13, v9
	v_min_i32_e32 v9, v13, v9
	v_max_i32_e32 v13, v48, v14
	v_min_i32_e32 v14, v48, v14
	v_max_i32_e32 v48, v2, v8
	v_min_i32_e32 v2, v2, v8
	v_max_i32_e32 v8, v5, v6
	v_min_i32_e32 v5, v5, v6
	v_max_i32_e32 v6, v15, v10
	v_min_i32_e32 v10, v15, v10
	v_max_i32_e32 v15, v4, v0
	v_min_i32_e32 v0, v4, v0
	v_max_i32_e32 v4, v1, v12
	v_min_i32_e32 v1, v1, v12
	v_max_i32_e32 v12, v7, v13
	v_min_i32_e32 v7, v7, v13
	v_max_i32_e32 v13, v3, v9
	v_min_i32_e32 v3, v3, v9
	v_max_i32_e32 v9, v11, v14
	v_min_i32_e32 v11, v11, v14
	v_max_i32_e32 v14, v48, v6
	v_min_i32_e32 v48, v48, v6
	v_max_i32_e32 v6, v8, v15
	v_min_i32_e32 v8, v8, v15
	v_max_i32_e32 v162, v2, v10
	v_min_i32_e32 v2, v2, v10
	v_max_i32_e32 v163, v5, v0
	v_min_i32_e32 v0, v5, v0
	v_max_i32_e32 v165, v4, v12
	v_min_i32_e32 v12, v4, v12
	v_max_i32_e32 v166, v1, v7
	v_min_i32_e32 v167, v1, v7
	v_max_i32_e32 v4, v13, v9
	v_min_i32_e32 v5, v13, v9
	v_max_i32_e32 v10, v3, v11
	v_min_i32_e32 v3, v3, v11
	v_max_i32_e32 v15, v14, v6
	v_min_i32_e32 v14, v14, v6
	v_max_i32_e32 v6, v48, v8
	v_min_i32_e32 v1, v48, v8
	v_max_i32_e32 v164, v162, v163
	v_min_i32_e32 v163, v162, v163
	v_max_i32_e32 v162, v2, v0
	v_min_i32_e32 v9, v2, v0
	v_ashrrev_i32_e32 v0, 31, v165
	v_and_b32_e32 v7, 0x7fffffff, v0
	v_bitop3_b32 v2, v0, v165, s75 bitop3:0x6c
	v_bitop3_b32 v0, v7, s80, v165 bitop3:0x48
	v_ashrrev_i32_e32 v165, 31, v4
	v_ashrrev_i32_e32 v7, 31, v12
	v_bitop3_b32 v165, v165, s80, v4 bitop3:0x48
	v_and_b32_e32 v8, 0x7fffffff, v7
	v_cndmask_b32_e64 v0, v0, v165, s[6:7]
	v_ashrrev_i32_e32 v165, 31, v5
	v_bitop3_b32 v8, v8, s80, v12 bitop3:0x48
	v_ashrrev_i32_e32 v11, 31, v166
	v_bitop3_b32 v165, v165, s80, v5 bitop3:0x48
	v_and_b32_e32 v13, 0x7fffffff, v11
	v_cndmask_b32_e64 v8, v8, v165, s[6:7]
	v_ashrrev_i32_e32 v165, 31, v10
	v_bitop3_b32 v7, v7, v12, s75 bitop3:0x6c
	v_bitop3_b32 v12, v11, v166, s75 bitop3:0x6c
	v_bitop3_b32 v11, v13, s80, v166 bitop3:0x48
	v_ashrrev_i32_e32 v13, 31, v167
	v_bitop3_b32 v165, v165, s80, v10 bitop3:0x48
	v_and_b32_e32 v48, 0x7fffffff, v13
	v_cndmask_b32_e64 v11, v11, v165, s[6:7]
	v_ashrrev_i32_e32 v165, 31, v3
	v_bitop3_b32 v48, v48, s80, v167 bitop3:0x48
	v_bitop3_b32 v165, v165, s80, v3 bitop3:0x48
	v_cndmask_b32_e64 v48, v48, v165, s[6:7]
	v_ashrrev_i32_e32 v165, 31, v15
	v_bitop3_b32 v165, v165, s80, v15 bitop3:0x48
	v_cndmask_b32_e64 v0, v0, v165, s[4:5]
	v_ashrrev_i32_e32 v165, 31, v14
	v_bitop3_b32 v165, v165, s80, v14 bitop3:0x48
	v_cndmask_b32_e64 v8, v8, v165, s[4:5]
	v_ashrrev_i32_e32 v165, 31, v6
	v_bitop3_b32 v165, v165, s80, v6 bitop3:0x48
	v_cndmask_b32_e64 v11, v11, v165, s[4:5]
	v_ashrrev_i32_e32 v165, 31, v1
	v_bitop3_b32 v165, v165, s80, v1 bitop3:0x48
	v_cndmask_b32_e64 v48, v48, v165, s[4:5]
	v_ashrrev_i32_e32 v165, 31, v164
	v_bitop3_b32 v165, v165, s80, v164 bitop3:0x48
	v_cndmask_b32_e64 v166, v0, v165, s[0:1]
	v_ashrrev_i32_e32 v0, 31, v163
	v_bitop3_b32 v0, v0, s80, v163 bitop3:0x48
	v_bitop3_b32 v13, v13, v167, s75 bitop3:0x6c
	v_cndmask_b32_e64 v167, v8, v0, s[0:1]
	v_ashrrev_i32_e32 v0, 31, v162
	v_bitop3_b32 v0, v0, s80, v162 bitop3:0x48
	v_cndmask_b32_e64 v168, v11, v0, s[0:1]
	v_ashrrev_i32_e32 v0, 31, v9
	v_bitop3_b32 v0, v0, s80, v9 bitop3:0x48
	v_cmp_gt_i32_e64 s[54:55], 0, v5
	v_cmp_gt_i32_e64 s[56:57], 0, v4
	v_cmp_gt_i32_e64 s[50:51], 0, v3
	v_cmp_gt_i32_e64 s[52:53], 0, v10
	v_cmp_gt_i32_e64 s[48:49], 0, v15
	v_cmp_gt_i32_e64 s[42:43], 0, v14
	v_cmp_gt_i32_e64 s[44:45], 0, v1
	v_cmp_gt_i32_e64 s[46:47], 0, v6
	v_cmp_gt_i32_e64 s[40:41], 0, v164
	v_cmp_gt_i32_e64 s[38:39], 0, v163
	v_cmp_gt_i32_e64 s[36:37], 0, v162
	v_cmp_gt_i32_e64 s[34:35], 0, v9
	v_cndmask_b32_e64 v169, v48, v0, s[0:1]
	v_cmp_lt_i32_e64 s[58:59], 1, v21
	ds_write_b128 v150, v[166:169] offset:64
	s_and_saveexec_b64 s[62:63], s[58:59]
	s_xor_b64 s[78:79], exec, s[62:63]
	s_cbranch_execz .LBB0_764
	v_cmp_lt_i32_e64 s[58:59], 2, v21
	s_and_saveexec_b64 s[62:63], s[58:59]
	s_xor_b64 s[58:59], exec, s[62:63]
	v_cndmask_b32_e64 v0, 0, v151, s[30:31]
	v_bitop3_b32 v48, v0, v160, s33 bitop3:0x78
	s_andn2_saveexec_b64 s[30:31], s[58:59]
	v_cndmask_b32_e64 v0, 0, v151, s[28:29]
	v_bitop3_b32 v48, v0, v159, s33 bitop3:0x78
	s_or_b64 exec, exec, s[30:31]

; __global__ void __launch_bounds__(256, 2) mega(P p) {
;   __shared__ __attribute__((aligned(16))) float lds_f[14340];
	.amdhsa_kernel _Z4mega1P
		.amdhsa_group_segment_fixed_size 78080
		.amdhsa_private_segment_fixed_size 0
		.amdhsa_kernarg_size 488
		.amdhsa_user_sgpr_count 2
		.amdhsa_user_sgpr_dispatch_ptr 0
		.amdhsa_user_sgpr_queue_ptr 0
		.amdhsa_user_sgpr_kernarg_segment_ptr 1
		.amdhsa_user_sgpr_dispatch_id 0
		.amdhsa_user_sgpr_kernarg_preload_length 0
		.amdhsa_user_sgpr_kernarg_preload_offset 0
		.amdhsa_user_sgpr_private_segment_size 0
		.amdhsa_uses_dynamic_stack 0
		.amdhsa_enable_private_segment 0
		.amdhsa_system_sgpr_workgroup_id_x 1
		.amdhsa_system_sgpr_workgroup_id_y 0
		.amdhsa_system_sgpr_workgroup_id_z 0
		.amdhsa_system_sgpr_workgroup_info 0
		.amdhsa_system_vgpr_workitem_id 2
		.amdhsa_next_free_vgpr 229
		.amdhsa_next_free_sgpr 98
		.amdhsa_accum_offset 232
		.amdhsa_reserve_vcc 1
		.amdhsa_float_round_mode_32 0
		.amdhsa_float_round_mode_16_64 0
		.amdhsa_float_denorm_mode_32 3
		.amdhsa_float_denorm_mode_16_64 3
		.amdhsa_dx10_clamp 1
		.amdhsa_ieee_mode 1
		.amdhsa_fp16_overflow 0
		.amdhsa_tg_split 0
		.amdhsa_exception_fp_ieee_invalid_op 0
		.amdhsa_exception_fp_denorm_src 0
		.amdhsa_exception_fp_ieee_div_zero 0
		.amdhsa_exception_fp_ieee_overflow 0
		.amdhsa_exception_fp_ieee_underflow 0
		.amdhsa_exception_fp_ieee_inexact 0
		.amdhsa_exception_int_div_zero 0
	.end_amdhsa_kernel

; __global__ void __launch_bounds__(256, 2) mega(P p) {
;   __shared__ __attribute__((aligned(16))) float lds_f[14340];
amdhsa.kernels:
  - .agpr_count:     0
    .args:
      - .offset:         0
        .size:           232
        .value_kind:     by_value
      - .offset:         232
        .size:           4
        .value_kind:     hidden_block_count_x
      - .offset:         236
        .size:           4
        .value_kind:     hidden_block_count_y
      - .offset:         240
        .size:           4
        .value_kind:     hidden_block_count_z
      - .offset:         244
        .size:           2
        .value_kind:     hidden_group_size_x
      - .offset:         246
        .size:           2
        .value_kind:     hidden_group_size_y
      - .offset:         248
        .size:           2
        .value_kind:     hidden_group_size_z
      - .offset:         250
        .size:           2
        .value_kind:     hidden_remainder_x
      - .offset:         252
        .size:           2
        .value_kind:     hidden_remainder_y
      - .offset:         254
        .size:           2
        .value_kind:     hidden_remainder_z
      - .offset:         272
        .size:           8
        .value_kind:     hidden_global_offset_x
      - .offset:         280
        .size:           8
        .value_kind:     hidden_global_offset_y
      - .offset:         288
        .size:           8
        .value_kind:     hidden_global_offset_z
      - .offset:         296
        .size:           2
        .value_kind:     hidden_grid_dims
      - .offset:         320
        .size:           8
        .value_kind:     hidden_multigrid_sync_arg
    .group_segment_fixed_size: 78080
    .kernarg_segment_align: 8
    .kernarg_segment_size: 488
    .language:       OpenCL C
    .language_version:
      - 2
      - 0
    .max_flat_workgroup_size: 256
    .name:           _Z4mega1P
    .private_segment_fixed_size: 0
    .sgpr_count:     104
    .sgpr_spill_count: 87
    .symbol:         _Z4mega1P.kd
    .uniform_work_group_size: 1
    .uses_dynamic_stack: false
    .vgpr_count:     229
    .vgpr_spill_count: 0
    .wavefront_size: 64
